# no L2 write-back at the barriers after P1,P3,P4,P5,P6 (all cross-workgroup stores of those phases are write-through; waves drain vmcnt before the workgroup barrier)
# speedup vs baseline: 1.0278x; 1.0070x over previous
; __device__ __forceinline__ unsigned xb_add(unsigned* p, unsigned v) { return __hip_atomic_fetch_add(p, v, __ATOMIC_RELAXED, __HIP_MEMORY_SCOPE_AGENT); }
; __device__ __forceinline__ void xcd_barrier(const XB& b) {
;     __syncthreads();
;     if (threadIdx.x == 0) {
;         unsigned* bar = b.bar;
;         __builtin_amdgcn_fence(__ATOMIC_RELEASE, "agent");
;         asm volatile("s_waitcnt vmcnt(0)" ::: "memory");
;         const unsigned old = xb_add(&bar[XB_XSUB(b.x)], 1u);
;         const unsigned gen = old / b.nloc;
;         if (old + 1u == (gen + 1u) * b.nloc) {
;             const unsigned og = xb_add(&bar[XB_TOP], 1u);
; template <int MODE>
; __device__ __forceinline__ void skinny(const Params& p, const h16* A, int lda, int row0, int nrt, const h16* Bt, int K, int nct) {
;     ...
;         if (MODE == SK_GATES) {
;             const float* bi = p.in[12]; const float* bf = p.in[13];
;             f32x4 o;
; #pragma unroll
;             for (int r = 0; r < 4; ++r) { const int cc = col + r; o[r] = acc[r] + (cc < 8 ? bi[cc] : bf[cc - 8]); }
;             *(f32x4*)((float*)(ws + OFF_GATES) + (size_t)row * 16 + col) = o;
.Lsk1_done:
	v_or_b32_e32 v6, v12, v138
	v_ashrrev_i32_e32 v7, 31, v6
	v_lshlrev_b64 v[8:9], 2, v[6:7]
	v_mov_b32_e32 v7, v141
	v_lshl_add_u64 v[14:15], v[6:7], 2, s[18:19]
	v_lshl_add_u64 v[12:13], s[16:17], 0, v[8:9]
	v_lshl_add_u64 v[16:17], v[14:15], 0, s[24:25]
	v_cmp_gt_i32_e32 vcc, 8, v6
	v_or_b32_e32 v7, 1, v6
	v_lshl_add_u64 v[18:19], v[12:13], 0, 4
	v_cndmask_b32_e32 v17, v17, v13, vcc
	v_cndmask_b32_e32 v16, v16, v12, vcc
	v_lshl_add_u64 v[20:21], v[14:15], 0, s[26:27]
	v_cmp_gt_i32_e32 vcc, 8, v7
	v_or_b32_e32 v7, 2, v6
	global_load_dword v16, v[16:17], off
	v_cndmask_b32_e32 v19, v21, v19, vcc
	v_cndmask_b32_e32 v18, v20, v18, vcc
	v_lshl_add_u64 v[20:21], v[12:13], 0, 8
	v_lshl_add_u64 v[22:23], v[14:15], 0, s[28:29]
	v_cmp_gt_i32_e32 vcc, 8, v7
	v_or_b32_e32 v17, 3, v6
	v_lshl_add_u64 v[6:7], v[12:13], 0, 12
	v_cndmask_b32_e32 v21, v23, v21, vcc
	v_cndmask_b32_e32 v20, v22, v20, vcc
	v_lshl_add_u64 v[12:13], v[14:15], 0, s[30:31]
	v_cmp_gt_i32_e32 vcc, 8, v17
	global_load_dword v20, v[20:21], off
	v_lshlrev_b64 v[4:5], 6, v[4:5]
	v_cndmask_b32_e32 v7, v13, v7, vcc
	v_cndmask_b32_e32 v6, v12, v6, vcc
	global_load_dword v21, v[6:7], off
	global_load_dword v17, v[18:19], off
	v_add_u32_e32 v11, v56, v11
	v_lshl_add_u64 v[4:5], s[6:7], 0, v[4:5]
	v_cmp_le_i32_e32 vcc, v55, v11
	v_lshl_add_u64 v[4:5], v[4:5], 0, v[8:9]
	s_or_b64 s[8:9], vcc, s[8:9]
	s_waitcnt vmcnt(0)
	v_pk_add_f32 v[2:3], v[2:3], v[20:21]
	v_pk_add_f32 v[0:1], v[0:1], v[16:17]
	global_store_dwordx4 v[4:5], v[0:3], off sc0 sc1
	s_andn2_b64 exec, exec, s[8:9]
	s_cbranch_execnz .LBB0_91
.LBB0_94:
	s_or_b64 exec, exec, s[0:1]
	s_max_u32 s92, s3, 1
	v_max_u32_e32 v133, 1, v10
	s_waitcnt vmcnt(0) lgkmcnt(0)
	s_waitcnt vmcnt(0)
	s_barrier
	s_mov_b64 s[0:1], exec
	v_readlane_b32 s6, v253, 2
	v_readlane_b32 s7, v253, 3
	s_and_b64 s[6:7], s[0:1], s[6:7]
	s_mov_b64 exec, s[6:7]
	s_cbranch_execz .LBB0_113
	s_mov_b64 s[8:9], exec
	s_nop 0
	s_waitcnt vmcnt(0)
	s_lshl_b32 s3, s89, 8
	v_readlane_b32 s6, v253, 0
	v_mbcnt_lo_u32_b32 v0, s8, 0
	v_readlane_b32 s7, v253, 1
	s_add_u32 s6, s6, s3
	v_mbcnt_hi_u32_b32 v0, s9, v0
	s_addc_u32 s7, s7, 0
	v_cmp_eq_u32_e32 vcc, 0, v0
	s_and_saveexec_b64 s[10:11], vcc
	s_cbranch_execz .LBB0_97
	s_bcnt1_i32_b64 s3, s[8:9]
	v_mov_b32_e32 v1, 0x1000
	v_mov_b32_e32 v2, s3
	global_atomic_add v1, v1, v2, s[6:7] sc0

; __device__ __forceinline__ float row_sum16(float x) { x = dpp_add<0xB1>(x); x = dpp_add<0x4E>(x); x = dpp_add<0x124>(x); x = dpp_add<0x128>(x); return x; }
; __device__ __forceinline__ void rwkv_sample_task(const Params& p, int s, int h) {
;     ...
;     const h16* ob = (const h16*)(ws + OFF_OPS16) + ((size_t)row * 8 + h) * 6 * 64;
;     f32x4 r4, d4, k4, a4, b4;
;     {
;         const h16x4 hr = *(const h16x4*)(ob + cg_ * 4), hw = *(const h16x4*)(ob + 64 + cg_ * 4), hk = *(const h16x4*)(ob + 128 + cg_ * 4),
;                     ha = *(const h16x4*)(ob + 256 + cg_ * 4), hb = *(const h16x4*)(ob + 320 + cg_ * 4);
; #pragma unroll
;         for (int j = 0; j < 4; ++j) { r4[j] = (float)hr[j]; d4[j] = __expf((float)hw[j]); k4[j] = (float)hk[j]; a4[j] = (float)ha[j]; b4[j] = (float)hb[j]; }
;     }
;     const float rk = ((const float*)(ws + OFF_RKS))[(size_t)row * 8 + h];
;     const float* S0 = p.in[6] + ((size_t)s * 8 + h) * 4096;
;     float* So = p.out + O_SS + ((size_t)s * 8 + h) * 4096;
;     float ysel = 0.f;
; #pragma unroll
;     for (int g = 0; g < 16; ++g) {
;         const int vrow = g * 4 + rr;
;         const float vv = (float)ob[192 + vrow];
;         f32x4 S = *(const f32x4*)(S0 + (size_t)vrow * 64 + cg_ * 4);
;         float sa = S[0] * a4[0] + S[1] * a4[1] + S[2] * a4[2] + S[3] * a4[3];
;         sa = row_sum16(sa);
;         S = S * d4 + sa * b4 + vv * k4;
;         float y = S[0] * r4[0] + S[1] * r4[1] + S[2] * r4[2] + S[3] * r4[3];
;         y = row_sum16(y) + rk * vv;
;         *(f32x4*)(So + (size_t)vrow * 64 + cg_ * 4) = S;
.LBB0_362:
	v_ashrrev_i32_e32 v0, 3, v143
	v_add_u32_e32 v106, 0x4000, v0
	v_ashrrev_i32_e32 v1, 31, v0
	v_ashrrev_i32_e32 v107, 31, v106
	v_lshlrev_b64 v[0:1], 17, v[0:1]
	v_lshlrev_b64 v[4:5], 3, v[106:107]
	v_mov_b64_e32 v[2:3], s[86:87]
	v_lshl_or_b32 v0, v56, 2, v0
	v_or_b32_e32 v4, v4, v54
	v_mov_b32_e32 v73, v53
	v_lshl_add_u64 v[146:147], v[58:59], 0, v[0:1]
	v_mad_u64_u32 v[150:151], s[0:1], v4, s3, v[2:3]
	v_lshl_add_u64 v[148:149], v[60:61], 0, v[0:1]
	v_lshl_add_u64 v[0:1], v[146:147], 0, v[72:73]
	v_mad_i32_i24 v151, v107, s3, v151
	v_mov_b32_e32 v71, v53
	global_load_dwordx4 v[0:3], v[0:1], off
	v_lshl_add_u64 v[10:11], v[150:151], 0, v[52:53]
	v_lshl_add_u64 v[4:5], v[4:5], 2, s[40:41]
	v_lshl_add_u64 v[6:7], v[148:149], 0, v[72:73]
	v_lshl_add_u64 v[126:127], v[150:151], 0, v[70:71]
	global_load_dwordx2 v[16:17], v[10:11], off offset:512
	global_load_dwordx2 v[18:19], v[10:11], off offset:128
	global_load_dwordx2 v[32:33], v[10:11], off offset:256
	global_load_dwordx2 v[34:35], v[10:11], off offset:640
	global_load_ushort v73, v[126:127], off offset:384
	global_load_dword v71, v[4:5], off
	global_load_dwordx2 v[108:109], v[10:11], off
	v_mov_b32_e32 v75, v53
	v_mov_b32_e32 v79, v53
	v_lshl_add_u64 v[8:9], v[146:147], 0, v[74:75]
	v_lshl_add_u64 v[22:23], v[146:147], 0, v[78:79]
	v_lshl_add_u64 v[24:25], v[148:149], 0, v[78:79]
	v_lshl_add_u64 v[12:13], v[148:149], 0, v[74:75]
	v_mov_b32_e32 v77, v53
	v_lshl_add_u64 v[14:15], v[146:147], 0, v[76:77]
	v_lshl_add_u64 v[20:21], v[148:149], 0, v[76:77]
	v_mov_b32_e32 v81, v53
	v_lshl_add_u64 v[26:27], v[146:147], 0, v[80:81]
	v_lshl_add_u64 v[28:29], v[148:149], 0, v[80:81]
	v_mov_b32_e32 v83, v53
	v_lshl_add_u64 v[30:31], v[146:147], 0, v[82:83]
	v_mov_b32_e32 v85, v53
	v_mov_b32_e32 v87, v53
	v_mov_b32_e32 v89, v53
	v_mov_b32_e32 v91, v53
	v_mov_b32_e32 v93, v53
	v_mov_b32_e32 v95, v53
	v_mov_b32_e32 v97, v53
	v_mov_b32_e32 v99, v53
	v_mov_b32_e32 v101, v53
	v_mov_b32_e32 v105, v53
	v_lshl_add_u64 v[162:163], v[148:149], 0, v[100:101]
	v_mov_b32_e32 v103, v53
	v_lshl_add_u64 v[150:151], v[150:151], 0, v[102:103]
	v_add_u32_e32 v143, s88, v143
	v_cmp_lt_i32_e64 s[0:1], s45, v143
	s_or_b64 s[42:43], s[0:1], s[42:43]
	s_waitcnt vmcnt(6)
	v_cvt_f32_f16_e32 v122, v16
	s_waitcnt vmcnt(5)
	v_cvt_f32_f16_e32 v5, v18
	v_cvt_f32_f16_sdwa v10, v18 dst_sel:DWORD dst_unused:UNUSED_PAD src0_sel:WORD_1
	v_cvt_f32_f16_e32 v11, v19
	v_cvt_f32_f16_sdwa v123, v16 dst_sel:DWORD dst_unused:UNUSED_PAD src0_sel:WORD_1
	v_cvt_f32_f16_e32 v124, v17
	v_cvt_f32_f16_sdwa v125, v17 dst_sel:DWORD dst_unused:UNUSED_PAD src0_sel:WORD_1
	s_waitcnt vmcnt(4)
	v_cvt_f32_f16_e32 v110, v32
	v_cvt_f32_f16_sdwa v111, v32 dst_sel:DWORD dst_unused:UNUSED_PAD src0_sel:WORD_1
	v_cvt_f32_f16_sdwa v18, v19 dst_sel:DWORD dst_unused:UNUSED_PAD src0_sel:WORD_1
	v_mul_f32_e32 v5, 0x3fb8aa3b, v5
	v_mul_f32_e32 v19, 0x3fb8aa3b, v10
	v_mul_f32_e32 v32, 0x3fb8aa3b, v11
	v_pk_mul_f32 v[10:11], v[0:1], v[122:123]
	v_pk_mul_f32 v[16:17], v[2:3], v[124:125]
	v_exp_f32_e32 v118, v5
	v_add_f32_e32 v5, v10, v11
	v_add_f32_e32 v5, v16, v5
	v_add_f32_e32 v5, v17, v5
	s_waitcnt vmcnt(3)
	v_cvt_f32_f16_e32 v112, v34
	v_cvt_f32_f16_sdwa v113, v34 dst_sel:DWORD dst_unused:UNUSED_PAD src0_sel:WORD_1
	v_cvt_f32_f16_e32 v116, v35
	v_cvt_f32_f16_sdwa v117, v35 dst_sel:DWORD dst_unused:UNUSED_PAD src0_sel:WORD_1
	v_mul_f32_e32 v18, 0x3fb8aa3b, v18
	v_add_f32_dpp v5, v5, v5 quad_perm:[1,0,3,2] row_mask:0xf bank_mask:0xf bound_ctrl:1
	v_exp_f32_e32 v119, v19
	v_exp_f32_e32 v120, v32
	v_exp_f32_e32 v121, v18
	v_add_f32_dpp v5, v5, v5 quad_perm:[2,3,0,1] row_mask:0xf bank_mask:0xf bound_ctrl:1
	v_cvt_f32_f16_e32 v114, v33
	v_cvt_f32_f16_sdwa v115, v33 dst_sel:DWORD dst_unused:UNUSED_PAD src0_sel:WORD_1
	s_waitcnt vmcnt(2)
	v_cvt_f32_f16_e32 v4, v73
	v_add_f32_dpp v5, v5, v5 row_ror:4 row_mask:0xf bank_mask:0xf bound_ctrl:1
	s_nop 1
	v_add_f32_dpp v10, v5, v5 row_ror:8 row_mask:0xf bank_mask:0xf bound_ctrl:1
	v_pk_mul_f32 v[16:17], v[116:117], v[10:11] op_sel_hi:[1,0]
	v_pk_mul_f32 v[10:11], v[112:113], v[10:11] op_sel_hi:[1,0]
	v_pk_fma_f32 v[2:3], v[2:3], v[120:121], v[16:17]
	v_pk_fma_f32 v[0:1], v[0:1], v[118:119], v[10:11]
	v_pk_fma_f32 v[2:3], v[114:115], v[4:5], v[2:3] op_sel_hi:[1,0,1]
	v_pk_fma_f32 v[0:1], v[110:111], v[4:5], v[0:1] op_sel_hi:[1,0,1]
	global_store_dwordx4 v[6:7], v[0:3], off sc0 sc1
	global_load_ushort v79, v[126:127], off offset:392
	s_nop 0
	global_load_dwordx4 v[4:7], v[8:9], off
	s_waitcnt vmcnt(1)
	v_cvt_f32_f16_e32 v8, v79
	s_waitcnt vmcnt(0)
	v_pk_mul_f32 v[10:11], v[4:5], v[122:123]
	v_pk_mul_f32 v[16:17], v[6:7], v[124:125]
	v_add_f32_e32 v9, v10, v11
	v_add_f32_e32 v9, v16, v9
	v_add_f32_e32 v9, v17, v9
	s_nop 1
	v_add_f32_dpp v9, v9, v9 quad_perm:[1,0,3,2] row_mask:0xf bank_mask:0xf bound_ctrl:1
	s_nop 1
	v_add_f32_dpp v9, v9, v9 quad_perm:[2,3,0,1] row_mask:0xf bank_mask:0xf bound_ctrl:1
	s_nop 1
	v_add_f32_dpp v9, v9, v9 row_ror:4 row_mask:0xf bank_mask:0xf bound_ctrl:1
	s_nop 1
	v_add_f32_dpp v10, v9, v9 row_ror:8 row_mask:0xf bank_mask:0xf bound_ctrl:1
	v_pk_mul_f32 v[16:17], v[116:117], v[10:11] op_sel_hi:[1,0]
	v_pk_mul_f32 v[10:11], v[112:113], v[10:11] op_sel_hi:[1,0]
	v_pk_fma_f32 v[6:7], v[120:121], v[6:7], v[16:17]
	v_pk_fma_f32 v[4:5], v[118:119], v[4:5], v[10:11]
	v_pk_fma_f32 v[10:11], v[114:115], v[8:9], v[6:7] op_sel_hi:[1,0,1]
	v_pk_fma_f32 v[8:9], v[110:111], v[8:9], v[4:5] op_sel_hi:[1,0,1]
	global_store_dwordx4 v[12:13], v[8:11], off sc0 sc1
	global_load_ushort v75, v[126:127], off offset:400
	global_load_dwordx4 v[4:7], v[14:15], off
	s_waitcnt vmcnt(1)
	v_cvt_f32_f16_e32 v12, v75
	s_waitcnt vmcnt(0)
; __device__ __forceinline__ float row_sum16(float x) { x = dpp_add<0xB1>(x); x = dpp_add<0x4E>(x); x = dpp_add<0x124>(x); x = dpp_add<0x128>(x); return x; }
; __device__ __forceinline__ void rwkv_sample_task(const Params& p, int s, int h) {
;     ...
; #pragma unroll
;     for (int g = 0; g < 16; ++g) {
;         const int vrow = g * 4 + rr;
;         const float vv = (float)ob[192 + vrow];
;         f32x4 S = *(const f32x4*)(S0 + (size_t)vrow * 64 + cg_ * 4);
;         float sa = S[0] * a4[0] + S[1] * a4[1] + S[2] * a4[2] + S[3] * a4[3];
;         sa = row_sum16(sa);
;         S = S * d4 + sa * b4 + vv * k4;
;         float y = S[0] * r4[0] + S[1] * r4[1] + S[2] * r4[2] + S[3] * r4[3];
;         y = row_sum16(y) + rk * vv;
;         *(f32x4*)(So + (size_t)vrow * 64 + cg_ * 4) = S;
;         ysel = (cg_ == g) ? y : ysel;
;     }
	v_pk_mul_f32 v[14:15], v[4:5], v[122:123]
	v_pk_mul_f32 v[16:17], v[6:7], v[124:125]
	v_add_f32_e32 v13, v14, v15
	v_add_f32_e32 v13, v16, v13
	v_add_f32_e32 v13, v17, v13
	s_nop 1
	v_add_f32_dpp v13, v13, v13 quad_perm:[1,0,3,2] row_mask:0xf bank_mask:0xf bound_ctrl:1
	s_nop 1
	v_add_f32_dpp v13, v13, v13 quad_perm:[2,3,0,1] row_mask:0xf bank_mask:0xf bound_ctrl:1
	s_nop 1
	v_add_f32_dpp v13, v13, v13 row_ror:4 row_mask:0xf bank_mask:0xf bound_ctrl:1
	s_nop 1
	v_add_f32_dpp v14, v13, v13 row_ror:8 row_mask:0xf bank_mask:0xf bound_ctrl:1
	v_pk_mul_f32 v[16:17], v[116:117], v[14:15] op_sel_hi:[1,0]
	v_pk_mul_f32 v[14:15], v[112:113], v[14:15] op_sel_hi:[1,0]
	v_pk_fma_f32 v[6:7], v[120:121], v[6:7], v[16:17]
	v_pk_fma_f32 v[4:5], v[118:119], v[4:5], v[14:15]
	v_pk_fma_f32 v[18:19], v[114:115], v[12:13], v[6:7] op_sel_hi:[1,0,1]
	v_pk_fma_f32 v[16:17], v[110:111], v[12:13], v[4:5] op_sel_hi:[1,0,1]
	global_store_dwordx4 v[20:21], v[16:19], off sc0 sc1
	global_load_ushort v77, v[126:127], off offset:408
	global_load_dwordx4 v[4:7], v[22:23], off
	s_waitcnt vmcnt(1)
	v_cvt_f32_f16_e32 v12, v77
	s_waitcnt vmcnt(0)
	v_pk_mul_f32 v[14:15], v[4:5], v[122:123]
	v_pk_mul_f32 v[20:21], v[6:7], v[124:125]
	v_add_f32_e32 v13, v14, v15
	v_add_f32_e32 v13, v20, v13
	v_add_f32_e32 v13, v21, v13
	s_nop 1
	v_add_f32_dpp v13, v13, v13 quad_perm:[1,0,3,2] row_mask:0xf bank_mask:0xf bound_ctrl:1
	s_nop 1
	v_add_f32_dpp v13, v13, v13 quad_perm:[2,3,0,1] row_mask:0xf bank_mask:0xf bound_ctrl:1
	s_nop 1
	v_add_f32_dpp v13, v13, v13 row_ror:4 row_mask:0xf bank_mask:0xf bound_ctrl:1
	s_nop 1
	v_add_f32_dpp v14, v13, v13 row_ror:8 row_mask:0xf bank_mask:0xf bound_ctrl:1
	v_pk_mul_f32 v[20:21], v[116:117], v[14:15] op_sel_hi:[1,0]
	v_pk_mul_f32 v[14:15], v[112:113], v[14:15] op_sel_hi:[1,0]
	v_pk_fma_f32 v[6:7], v[120:121], v[6:7], v[20:21]
	v_pk_fma_f32 v[4:5], v[118:119], v[4:5], v[14:15]
	v_pk_fma_f32 v[6:7], v[114:115], v[12:13], v[6:7] op_sel_hi:[1,0,1]
	v_pk_fma_f32 v[4:5], v[110:111], v[12:13], v[4:5] op_sel_hi:[1,0,1]
	global_store_dwordx4 v[24:25], v[4:7], off sc0 sc1
	global_load_dwordx4 v[12:15], v[26:27], off
	global_load_ushort v81, v[126:127], off offset:416
	v_lshl_add_u64 v[26:27], v[146:147], 0, v[84:85]
	s_waitcnt vmcnt(1)
	v_pk_mul_f32 v[22:23], v[12:13], v[122:123]
	v_pk_mul_f32 v[24:25], v[14:15], v[124:125]
	v_add_f32_e32 v21, v22, v23
	v_add_f32_e32 v21, v24, v21
	v_add_f32_e32 v21, v25, v21
	s_waitcnt vmcnt(0)
	v_cvt_f32_f16_e32 v20, v81
	v_add_f32_dpp v21, v21, v21 quad_perm:[1,0,3,2] row_mask:0xf bank_mask:0xf bound_ctrl:1
	s_nop 1
	v_add_f32_dpp v21, v21, v21 quad_perm:[2,3,0,1] row_mask:0xf bank_mask:0xf bound_ctrl:1
	s_nop 1
	v_add_f32_dpp v21, v21, v21 row_ror:4 row_mask:0xf bank_mask:0xf bound_ctrl:1
	s_nop 1
	v_add_f32_dpp v22, v21, v21 row_ror:8 row_mask:0xf bank_mask:0xf bound_ctrl:1
	v_pk_mul_f32 v[24:25], v[116:117], v[22:23] op_sel_hi:[1,0]
	v_pk_mul_f32 v[22:23], v[112:113], v[22:23] op_sel_hi:[1,0]
	v_pk_fma_f32 v[14:15], v[120:121], v[14:15], v[24:25]
	v_pk_fma_f32 v[12:13], v[118:119], v[12:13], v[22:23]
	v_pk_fma_f32 v[14:15], v[114:115], v[20:21], v[14:15] op_sel_hi:[1,0,1]
	v_pk_fma_f32 v[12:13], v[110:111], v[20:21], v[12:13] op_sel_hi:[1,0,1]
	global_store_dwordx4 v[28:29], v[12:15], off sc0 sc1
	global_load_dwordx4 v[20:23], v[30:31], off
	global_load_ushort v145, v[126:127], off offset:424
	v_lshl_add_u64 v[24:25], v[148:149], 0, v[82:83]
	s_waitcnt vmcnt(1)
	v_pk_mul_f32 v[30:31], v[20:21], v[122:123]
	v_pk_mul_f32 v[32:33], v[22:23], v[124:125]
	v_add_f32_e32 v29, v30, v31
	v_add_f32_e32 v29, v32, v29
	v_add_f32_e32 v29, v33, v29
	s_waitcnt vmcnt(0)
	v_cvt_f32_f16_e32 v28, v145
	v_add_f32_dpp v29, v29, v29 quad_perm:[1,0,3,2] row_mask:0xf bank_mask:0xf bound_ctrl:1
	s_nop 1
	v_add_f32_dpp v29, v29, v29 quad_perm:[2,3,0,1] row_mask:0xf bank_mask:0xf bound_ctrl:1
	s_nop 1
	v_add_f32_dpp v29, v29, v29 row_ror:4 row_mask:0xf bank_mask:0xf bound_ctrl:1
	s_nop 1
	v_add_f32_dpp v30, v29, v29 row_ror:8 row_mask:0xf bank_mask:0xf bound_ctrl:1
	v_pk_mul_f32 v[32:33], v[116:117], v[30:31] op_sel_hi:[1,0]
	v_pk_mul_f32 v[30:31], v[112:113], v[30:31] op_sel_hi:[1,0]
	v_pk_fma_f32 v[22:23], v[120:121], v[22:23], v[32:33]
	v_pk_fma_f32 v[20:21], v[118:119], v[20:21], v[30:31]
	v_pk_fma_f32 v[22:23], v[114:115], v[28:29], v[22:23] op_sel_hi:[1,0,1]
	v_pk_fma_f32 v[20:21], v[110:111], v[28:29], v[20:21] op_sel_hi:[1,0,1]
	global_store_dwordx4 v[24:25], v[20:23], off sc0 sc1
	global_load_dwordx4 v[24:27], v[26:27], off
	s_nop 0
	global_load_ushort v83, v[126:127], off offset:432
	v_lshl_add_u64 v[28:29], v[148:149], 0, v[84:85]
	v_lshl_add_u64 v[30:31], v[146:147], 0, v[86:87]
	s_waitcnt vmcnt(1)
	v_pk_mul_f32 v[34:35], v[24:25], v[122:123]
	v_pk_mul_f32 v[36:37], v[26:27], v[124:125]
	v_add_f32_e32 v33, v34, v35
	v_add_f32_e32 v33, v36, v33
	v_add_f32_e32 v33, v37, v33
	s_waitcnt vmcnt(0)
	v_cvt_f32_f16_e32 v32, v83
	v_add_f32_dpp v33, v33, v33 quad_perm:[1,0,3,2] row_mask:0xf bank_mask:0xf bound_ctrl:1
	s_nop 1
	v_add_f32_dpp v33, v33, v33 quad_perm:[2,3,0,1] row_mask:0xf bank_mask:0xf bound_ctrl:1
	s_nop 1
	v_add_f32_dpp v33, v33, v33 row_ror:4 row_mask:0xf bank_mask:0xf bound_ctrl:1
	s_nop 1
	v_add_f32_dpp v34, v33, v33 row_ror:8 row_mask:0xf bank_mask:0xf bound_ctrl:1
	v_pk_mul_f32 v[36:37], v[116:117], v[34:35] op_sel_hi:[1,0]
	v_pk_mul_f32 v[34:35], v[112:113], v[34:35] op_sel_hi:[1,0]
	v_pk_fma_f32 v[26:27], v[120:121], v[26:27], v[36:37]
	v_pk_fma_f32 v[24:25], v[118:119], v[24:25], v[34:35]
	v_pk_fma_f32 v[26:27], v[114:115], v[32:33], v[26:27] op_sel_hi:[1,0,1]
	v_pk_fma_f32 v[24:25], v[110:111], v[32:33], v[24:25] op_sel_hi:[1,0,1]
	global_store_dwordx4 v[28:29], v[24:27], off sc0 sc1
	global_load_dwordx4 v[28:31], v[30:31], off
	s_nop 0
	global_load_ushort v85, v[126:127], off offset:440
	v_lshl_add_u64 v[32:33], v[148:149], 0, v[86:87]
	v_lshl_add_u64 v[34:35], v[146:147], 0, v[88:89]
	s_waitcnt vmcnt(1)
; __device__ __forceinline__ float row_sum16(float x) { x = dpp_add<0xB1>(x); x = dpp_add<0x4E>(x); x = dpp_add<0x124>(x); x = dpp_add<0x128>(x); return x; }
; __device__ __forceinline__ void rwkv_sample_task(const Params& p, int s, int h) {
;     ...
; #pragma unroll
;     for (int g = 0; g < 16; ++g) {
;         const int vrow = g * 4 + rr;
;         const float vv = (float)ob[192 + vrow];
;         f32x4 S = *(const f32x4*)(S0 + (size_t)vrow * 64 + cg_ * 4);
;         float sa = S[0] * a4[0] + S[1] * a4[1] + S[2] * a4[2] + S[3] * a4[3];
;         sa = row_sum16(sa);
;         S = S * d4 + sa * b4 + vv * k4;
;         float y = S[0] * r4[0] + S[1] * r4[1] + S[2] * r4[2] + S[3] * r4[3];
;         y = row_sum16(y) + rk * vv;
;         *(f32x4*)(So + (size_t)vrow * 64 + cg_ * 4) = S;
;         ysel = (cg_ == g) ? y : ysel;
;     }
	v_pk_mul_f32 v[38:39], v[28:29], v[122:123]
	v_pk_mul_f32 v[40:41], v[30:31], v[124:125]
	v_add_f32_e32 v37, v38, v39
	v_add_f32_e32 v37, v40, v37
	v_add_f32_e32 v37, v41, v37
	s_waitcnt vmcnt(0)
	v_cvt_f32_f16_e32 v36, v85
	v_add_f32_dpp v37, v37, v37 quad_perm:[1,0,3,2] row_mask:0xf bank_mask:0xf bound_ctrl:1
	s_nop 1
	v_add_f32_dpp v37, v37, v37 quad_perm:[2,3,0,1] row_mask:0xf bank_mask:0xf bound_ctrl:1
	s_nop 1
	v_add_f32_dpp v37, v37, v37 row_ror:4 row_mask:0xf bank_mask:0xf bound_ctrl:1
	s_nop 1
	v_add_f32_dpp v38, v37, v37 row_ror:8 row_mask:0xf bank_mask:0xf bound_ctrl:1
	v_pk_mul_f32 v[40:41], v[116:117], v[38:39] op_sel_hi:[1,0]
	v_pk_mul_f32 v[38:39], v[112:113], v[38:39] op_sel_hi:[1,0]
	v_pk_fma_f32 v[30:31], v[120:121], v[30:31], v[40:41]
	v_pk_fma_f32 v[28:29], v[118:119], v[28:29], v[38:39]
	v_pk_fma_f32 v[30:31], v[114:115], v[36:37], v[30:31] op_sel_hi:[1,0,1]
	v_pk_fma_f32 v[28:29], v[110:111], v[36:37], v[28:29] op_sel_hi:[1,0,1]
	global_store_dwordx4 v[32:33], v[28:31], off sc0 sc1
	global_load_dwordx4 v[32:35], v[34:35], off
	s_nop 0
	global_load_ushort v87, v[126:127], off offset:448
	v_lshl_add_u64 v[36:37], v[148:149], 0, v[88:89]
	v_lshl_add_u64 v[38:39], v[146:147], 0, v[90:91]
	s_waitcnt vmcnt(1)
	v_pk_mul_f32 v[42:43], v[32:33], v[122:123]
	v_pk_mul_f32 v[44:45], v[34:35], v[124:125]
	v_add_f32_e32 v41, v42, v43
	v_add_f32_e32 v41, v44, v41
	v_add_f32_e32 v41, v45, v41
	s_waitcnt vmcnt(0)
	v_cvt_f32_f16_e32 v40, v87
	v_add_f32_dpp v41, v41, v41 quad_perm:[1,0,3,2] row_mask:0xf bank_mask:0xf bound_ctrl:1
	s_nop 1
	v_add_f32_dpp v41, v41, v41 quad_perm:[2,3,0,1] row_mask:0xf bank_mask:0xf bound_ctrl:1
	s_nop 1
	v_add_f32_dpp v41, v41, v41 row_ror:4 row_mask:0xf bank_mask:0xf bound_ctrl:1
	s_nop 1
	v_add_f32_dpp v42, v41, v41 row_ror:8 row_mask:0xf bank_mask:0xf bound_ctrl:1
	v_pk_mul_f32 v[44:45], v[116:117], v[42:43] op_sel_hi:[1,0]
	v_pk_mul_f32 v[42:43], v[112:113], v[42:43] op_sel_hi:[1,0]
	v_pk_fma_f32 v[34:35], v[120:121], v[34:35], v[44:45]
	v_pk_fma_f32 v[32:33], v[118:119], v[32:33], v[42:43]
	v_pk_fma_f32 v[34:35], v[114:115], v[40:41], v[34:35] op_sel_hi:[1,0,1]
	v_pk_fma_f32 v[32:33], v[110:111], v[40:41], v[32:33] op_sel_hi:[1,0,1]
	global_store_dwordx4 v[36:37], v[32:35], off sc0 sc1
	global_load_dwordx4 v[36:39], v[38:39], off
	s_nop 0
	global_load_ushort v89, v[126:127], off offset:456
	v_lshl_add_u64 v[40:41], v[148:149], 0, v[90:91]
	v_lshl_add_u64 v[42:43], v[146:147], 0, v[92:93]
	s_waitcnt vmcnt(1)
	v_pk_mul_f32 v[46:47], v[36:37], v[122:123]
	v_pk_mul_f32 v[48:49], v[38:39], v[124:125]
	v_add_f32_e32 v45, v46, v47
	v_add_f32_e32 v45, v48, v45
	v_add_f32_e32 v45, v49, v45
	s_waitcnt vmcnt(0)
	v_cvt_f32_f16_e32 v44, v89
	v_add_f32_dpp v45, v45, v45 quad_perm:[1,0,3,2] row_mask:0xf bank_mask:0xf bound_ctrl:1
	s_nop 1
	v_add_f32_dpp v45, v45, v45 quad_perm:[2,3,0,1] row_mask:0xf bank_mask:0xf bound_ctrl:1
	s_nop 1
	v_add_f32_dpp v45, v45, v45 row_ror:4 row_mask:0xf bank_mask:0xf bound_ctrl:1
	s_nop 1
	v_add_f32_dpp v46, v45, v45 row_ror:8 row_mask:0xf bank_mask:0xf bound_ctrl:1
	v_pk_mul_f32 v[48:49], v[116:117], v[46:47] op_sel_hi:[1,0]
	v_pk_mul_f32 v[46:47], v[112:113], v[46:47] op_sel_hi:[1,0]
	v_pk_fma_f32 v[38:39], v[120:121], v[38:39], v[48:49]
	v_pk_fma_f32 v[36:37], v[118:119], v[36:37], v[46:47]
	v_pk_fma_f32 v[38:39], v[114:115], v[44:45], v[38:39] op_sel_hi:[1,0,1]
	v_pk_fma_f32 v[36:37], v[110:111], v[44:45], v[36:37] op_sel_hi:[1,0,1]
	global_store_dwordx4 v[40:41], v[36:39], off sc0 sc1
	global_load_dwordx4 v[40:43], v[42:43], off
	s_nop 0
	global_load_ushort v91, v[126:127], off offset:464
	v_lshl_add_u64 v[44:45], v[148:149], 0, v[92:93]
	v_lshl_add_u64 v[46:47], v[146:147], 0, v[94:95]
	s_waitcnt vmcnt(1)
	v_pk_mul_f32 v[50:51], v[40:41], v[122:123]
	v_pk_mul_f32 v[152:153], v[42:43], v[124:125]
	v_add_f32_e32 v49, v50, v51
	v_add_f32_e32 v49, v152, v49
	v_add_f32_e32 v49, v153, v49
	s_waitcnt vmcnt(0)
	v_cvt_f32_f16_e32 v48, v91
	v_add_f32_dpp v49, v49, v49 quad_perm:[1,0,3,2] row_mask:0xf bank_mask:0xf bound_ctrl:1
	s_nop 1
	v_add_f32_dpp v49, v49, v49 quad_perm:[2,3,0,1] row_mask:0xf bank_mask:0xf bound_ctrl:1
	s_nop 1
	v_add_f32_dpp v49, v49, v49 row_ror:4 row_mask:0xf bank_mask:0xf bound_ctrl:1
	s_nop 1
	v_add_f32_dpp v50, v49, v49 row_ror:8 row_mask:0xf bank_mask:0xf bound_ctrl:1
	v_pk_mul_f32 v[152:153], v[116:117], v[50:51] op_sel_hi:[1,0]
	v_pk_mul_f32 v[50:51], v[112:113], v[50:51] op_sel_hi:[1,0]
	v_pk_fma_f32 v[42:43], v[120:121], v[42:43], v[152:153]
	v_pk_fma_f32 v[40:41], v[118:119], v[40:41], v[50:51]
	v_pk_fma_f32 v[42:43], v[114:115], v[48:49], v[42:43] op_sel_hi:[1,0,1]
	v_pk_fma_f32 v[40:41], v[110:111], v[48:49], v[40:41] op_sel_hi:[1,0,1]
	global_store_dwordx4 v[44:45], v[40:43], off sc0 sc1
	global_load_dwordx4 v[44:47], v[46:47], off
	s_nop 0
	global_load_ushort v93, v[126:127], off offset:472
	v_lshl_add_u64 v[48:49], v[148:149], 0, v[94:95]
	v_lshl_add_u64 v[50:51], v[146:147], 0, v[96:97]
	s_waitcnt vmcnt(1)
	v_pk_mul_f32 v[154:155], v[44:45], v[122:123]
	v_pk_mul_f32 v[156:157], v[46:47], v[124:125]
	v_add_f32_e32 v95, v154, v155
	v_add_f32_e32 v95, v156, v95
	v_add_f32_e32 v95, v157, v95
	s_waitcnt vmcnt(0)
; __device__ __forceinline__ float row_sum16(float x) { x = dpp_add<0xB1>(x); x = dpp_add<0x4E>(x); x = dpp_add<0x124>(x); x = dpp_add<0x128>(x); return x; }
; __device__ __forceinline__ void rwkv_sample_task(const Params& p, int s, int h) {
;     ...
; #pragma unroll
;     for (int g = 0; g < 16; ++g) {
;         const int vrow = g * 4 + rr;
;         const float vv = (float)ob[192 + vrow];
;         f32x4 S = *(const f32x4*)(S0 + (size_t)vrow * 64 + cg_ * 4);
;         float sa = S[0] * a4[0] + S[1] * a4[1] + S[2] * a4[2] + S[3] * a4[3];
;         sa = row_sum16(sa);
;         S = S * d4 + sa * b4 + vv * k4;
;         float y = S[0] * r4[0] + S[1] * r4[1] + S[2] * r4[2] + S[3] * r4[3];
;         y = row_sum16(y) + rk * vv;
;         *(f32x4*)(So + (size_t)vrow * 64 + cg_ * 4) = S;
;         ysel = (cg_ == g) ? y : ysel;
;     }
	v_cvt_f32_f16_e32 v152, v93
	v_add_f32_dpp v95, v95, v95 quad_perm:[1,0,3,2] row_mask:0xf bank_mask:0xf bound_ctrl:1
	s_nop 1
	v_add_f32_dpp v95, v95, v95 quad_perm:[2,3,0,1] row_mask:0xf bank_mask:0xf bound_ctrl:1
	s_nop 1
	v_add_f32_dpp v95, v95, v95 row_ror:4 row_mask:0xf bank_mask:0xf bound_ctrl:1
	s_nop 1
	v_add_f32_dpp v154, v95, v95 row_ror:8 row_mask:0xf bank_mask:0xf bound_ctrl:1
	v_pk_mul_f32 v[156:157], v[116:117], v[154:155] op_sel_hi:[1,0]
	v_pk_mul_f32 v[154:155], v[112:113], v[154:155] op_sel_hi:[1,0]
	v_pk_fma_f32 v[46:47], v[120:121], v[46:47], v[156:157]
	v_pk_fma_f32 v[44:45], v[118:119], v[44:45], v[154:155]
	v_pk_fma_f32 v[46:47], v[114:115], v[152:153], v[46:47] op_sel_hi:[1,0,1]
	v_pk_fma_f32 v[44:45], v[110:111], v[152:153], v[44:45] op_sel_hi:[1,0,1]
	global_store_dwordx4 v[48:49], v[44:47], off sc0 sc1
	global_load_dwordx4 v[48:51], v[50:51], off
	s_nop 0
	global_load_ushort v95, v[126:127], off offset:480
	v_lshl_add_u64 v[152:153], v[148:149], 0, v[96:97]
	v_lshl_add_u64 v[154:155], v[146:147], 0, v[98:99]
	s_waitcnt vmcnt(1)
	v_pk_mul_f32 v[158:159], v[48:49], v[122:123]
	v_pk_mul_f32 v[160:161], v[50:51], v[124:125]
	v_add_f32_e32 v97, v158, v159
	v_add_f32_e32 v97, v160, v97
	v_add_f32_e32 v97, v161, v97
	s_waitcnt vmcnt(0)
	v_cvt_f32_f16_e32 v156, v95
	v_add_f32_dpp v97, v97, v97 quad_perm:[1,0,3,2] row_mask:0xf bank_mask:0xf bound_ctrl:1
	s_nop 1
	v_add_f32_dpp v97, v97, v97 quad_perm:[2,3,0,1] row_mask:0xf bank_mask:0xf bound_ctrl:1
	s_nop 1
	v_add_f32_dpp v97, v97, v97 row_ror:4 row_mask:0xf bank_mask:0xf bound_ctrl:1
	s_nop 1
	v_add_f32_dpp v158, v97, v97 row_ror:8 row_mask:0xf bank_mask:0xf bound_ctrl:1
	v_pk_mul_f32 v[160:161], v[116:117], v[158:159] op_sel_hi:[1,0]
	v_pk_mul_f32 v[158:159], v[112:113], v[158:159] op_sel_hi:[1,0]
	v_pk_fma_f32 v[50:51], v[120:121], v[50:51], v[160:161]
	v_pk_fma_f32 v[48:49], v[118:119], v[48:49], v[158:159]
	v_pk_fma_f32 v[50:51], v[114:115], v[156:157], v[50:51] op_sel_hi:[1,0,1]
	v_pk_fma_f32 v[48:49], v[110:111], v[156:157], v[48:49] op_sel_hi:[1,0,1]
	global_store_dwordx4 v[152:153], v[48:51], off sc0 sc1
	global_load_dwordx4 v[152:155], v[154:155], off
	s_nop 0
	global_load_ushort v97, v[126:127], off offset:488
	v_lshl_add_u64 v[158:159], v[148:149], 0, v[98:99]
	v_cvt_f32_f16_sdwa v99, v108 dst_sel:DWORD dst_unused:UNUSED_PAD src0_sel:WORD_1
	v_lshl_add_u64 v[160:161], v[146:147], 0, v[100:101]
	v_lshl_add_u64 v[146:147], v[146:147], 0, v[104:105]
	v_lshl_add_u64 v[148:149], v[148:149], 0, v[104:105]
	v_mul_f32_e32 v1, v1, v99
	v_fma_mix_f32 v0, v0, v108, v1 op_sel_hi:[0,1,0]
	v_mul_f32_e32 v1, v9, v99
	v_fma_mix_f32 v0, v2, v109, v0 op_sel_hi:[0,1,0]
	v_fma_mix_f32 v1, v8, v108, v1 op_sel_hi:[0,1,0]
	v_fma_mix_f32 v0, v3, v109, v0 op_sel:[0,1,0] op_sel_hi:[0,1,0]
	v_fma_mix_f32 v1, v10, v109, v1 op_sel_hi:[0,1,0]
	v_fma_mix_f32 v1, v11, v109, v1 op_sel:[0,1,0] op_sel_hi:[0,1,0]
	v_add_f32_dpp v0, v0, v0 quad_perm:[1,0,3,2] row_mask:0xf bank_mask:0xf bound_ctrl:1
	v_mul_f32_e32 v5, v5, v99
	v_add_f32_dpp v1, v1, v1 quad_perm:[1,0,3,2] row_mask:0xf bank_mask:0xf bound_ctrl:1
	v_add_f32_dpp v0, v0, v0 quad_perm:[2,3,0,1] row_mask:0xf bank_mask:0xf bound_ctrl:1
	v_fma_mix_f32 v4, v4, v108, v5 op_sel_hi:[0,1,0]
	v_add_f32_dpp v1, v1, v1 quad_perm:[2,3,0,1] row_mask:0xf bank_mask:0xf bound_ctrl:1
	v_add_f32_dpp v0, v0, v0 row_ror:4 row_mask:0xf bank_mask:0xf bound_ctrl:1
	v_mul_f32_e32 v5, v13, v99
	v_add_f32_dpp v1, v1, v1 row_ror:4 row_mask:0xf bank_mask:0xf bound_ctrl:1
	v_add_f32_dpp v0, v0, v0 row_ror:8 row_mask:0xf bank_mask:0xf bound_ctrl:1
	v_fma_mix_f32 v0, v71, v73, v0 op_sel_hi:[0,1,0]
	v_add_f32_dpp v1, v1, v1 row_ror:8 row_mask:0xf bank_mask:0xf bound_ctrl:1
	v_cndmask_b32_e32 v0, 0, v0, vcc
	v_fma_mix_f32 v1, v71, v79, v1 op_sel_hi:[0,1,0]
	v_cndmask_b32_e64 v73, v0, v1, s[4:5]
	v_mul_f32_e32 v0, v17, v99
	v_fma_mix_f32 v0, v16, v108, v0 op_sel_hi:[0,1,0]
	v_fma_mix_f32 v0, v18, v109, v0 op_sel_hi:[0,1,0]
	v_fma_mix_f32 v16, v19, v109, v0 op_sel:[0,1,0] op_sel_hi:[0,1,0]
	v_fma_mix_f32 v4, v6, v109, v4 op_sel_hi:[0,1,0]
	v_fma_mix_f32 v5, v12, v108, v5 op_sel_hi:[0,1,0]
	v_add_f32_dpp v16, v16, v16 quad_perm:[1,0,3,2] row_mask:0xf bank_mask:0xf bound_ctrl:1
	v_fma_mix_f32 v4, v7, v109, v4 op_sel:[0,1,0] op_sel_hi:[0,1,0]
	v_fma_mix_f32 v5, v14, v109, v5 op_sel_hi:[0,1,0]
	v_add_f32_dpp v16, v16, v16 quad_perm:[2,3,0,1] row_mask:0xf bank_mask:0xf bound_ctrl:1
	v_add_f32_dpp v4, v4, v4 quad_perm:[1,0,3,2] row_mask:0xf bank_mask:0xf bound_ctrl:1
	v_fma_mix_f32 v5, v15, v109, v5 op_sel:[0,1,0] op_sel_hi:[0,1,0]
	v_add_f32_dpp v16, v16, v16 row_ror:4 row_mask:0xf bank_mask:0xf bound_ctrl:1
	v_add_f32_dpp v4, v4, v4 quad_perm:[2,3,0,1] row_mask:0xf bank_mask:0xf bound_ctrl:1
	v_add_f32_dpp v5, v5, v5 quad_perm:[1,0,3,2] row_mask:0xf bank_mask:0xf bound_ctrl:1
	v_add_f32_dpp v16, v16, v16 row_ror:8 row_mask:0xf bank_mask:0xf bound_ctrl:1
	v_add_f32_dpp v4, v4, v4 row_ror:4 row_mask:0xf bank_mask:0xf bound_ctrl:1
	v_add_f32_dpp v5, v5, v5 quad_perm:[2,3,0,1] row_mask:0xf bank_mask:0xf bound_ctrl:1
	v_fma_mix_f32 v16, v71, v75, v16 op_sel_hi:[0,1,0]
	v_add_f32_dpp v4, v4, v4 row_ror:8 row_mask:0xf bank_mask:0xf bound_ctrl:1
	v_add_f32_dpp v5, v5, v5 row_ror:4 row_mask:0xf bank_mask:0xf bound_ctrl:1
	v_cndmask_b32_e64 v16, v73, v16, s[6:7]
	v_fma_mix_f32 v4, v71, v77, v4 op_sel_hi:[0,1,0]
	v_add_f32_dpp v5, v5, v5 row_ror:8 row_mask:0xf bank_mask:0xf bound_ctrl:1
	v_cndmask_b32_e64 v4, v16, v4, s[8:9]
	v_fma_mix_f32 v5, v71, v81, v5 op_sel_hi:[0,1,0]
	v_cndmask_b32_e64 v4, v4, v5, s[10:11]
	v_mul_f32_e32 v5, v21, v99
	v_fma_mix_f32 v5, v20, v108, v5 op_sel_hi:[0,1,0]
	v_fma_mix_f32 v5, v22, v109, v5 op_sel_hi:[0,1,0]
	v_fma_mix_f32 v5, v23, v109, v5 op_sel:[0,1,0] op_sel_hi:[0,1,0]
	v_lshlrev_b64 v[156:157], 10, v[106:107]
	v_lshl_add_u64 v[156:157], v[64:65], 0, v[156:157]
	v_add_f32_dpp v5, v5, v5 quad_perm:[1,0,3,2] row_mask:0xf bank_mask:0xf bound_ctrl:1
	s_waitcnt vmcnt(1)
; __device__ __forceinline__ float row_sum16(float x) { x = dpp_add<0xB1>(x); x = dpp_add<0x4E>(x); x = dpp_add<0x124>(x); x = dpp_add<0x128>(x); return x; }
; __device__ __forceinline__ void rwkv_sample_task(const Params& p, int s, int h) {
;     ...
; #pragma unroll
;     for (int g = 0; g < 16; ++g) {
;         const int vrow = g * 4 + rr;
;         const float vv = (float)ob[192 + vrow];
;         f32x4 S = *(const f32x4*)(S0 + (size_t)vrow * 64 + cg_ * 4);
;         float sa = S[0] * a4[0] + S[1] * a4[1] + S[2] * a4[2] + S[3] * a4[3];
;         sa = row_sum16(sa);
;         S = S * d4 + sa * b4 + vv * k4;
;         float y = S[0] * r4[0] + S[1] * r4[1] + S[2] * r4[2] + S[3] * r4[3];
;         y = row_sum16(y) + rk * vv;
;         *(f32x4*)(So + (size_t)vrow * 64 + cg_ * 4) = S;
;         ysel = (cg_ == g) ? y : ysel;
;     }
	v_pk_mul_f32 v[2:3], v[152:153], v[122:123]
	v_pk_mul_f32 v[8:9], v[154:155], v[124:125]
	v_add_f32_e32 v1, v2, v3
	v_add_f32_e32 v1, v8, v1
	v_add_f32_e32 v1, v9, v1
	s_waitcnt vmcnt(0)
	v_cvt_f32_f16_e32 v0, v97
	v_add_f32_dpp v5, v5, v5 quad_perm:[2,3,0,1] row_mask:0xf bank_mask:0xf bound_ctrl:1
	v_add_f32_dpp v1, v1, v1 quad_perm:[1,0,3,2] row_mask:0xf bank_mask:0xf bound_ctrl:1
	s_nop 0
	v_add_f32_dpp v5, v5, v5 row_ror:4 row_mask:0xf bank_mask:0xf bound_ctrl:1
	v_add_f32_dpp v1, v1, v1 quad_perm:[2,3,0,1] row_mask:0xf bank_mask:0xf bound_ctrl:1
	s_nop 0
	v_add_f32_dpp v5, v5, v5 row_ror:8 row_mask:0xf bank_mask:0xf bound_ctrl:1
	v_add_f32_dpp v1, v1, v1 row_ror:4 row_mask:0xf bank_mask:0xf bound_ctrl:1
	v_fma_mix_f32 v5, v71, v145, v5 op_sel_hi:[0,1,0]
	v_cndmask_b32_e64 v4, v4, v5, s[12:13]
	v_add_f32_dpp v2, v1, v1 row_ror:8 row_mask:0xf bank_mask:0xf bound_ctrl:1
	v_pk_mul_f32 v[8:9], v[116:117], v[2:3] op_sel_hi:[1,0]
	v_pk_mul_f32 v[2:3], v[112:113], v[2:3] op_sel_hi:[1,0]
	v_mul_f32_e32 v5, v25, v99
	v_pk_fma_f32 v[10:11], v[118:119], v[152:153], v[2:3]
	v_pk_fma_f32 v[2:3], v[120:121], v[154:155], v[8:9]
	v_fma_mix_f32 v5, v24, v108, v5 op_sel_hi:[0,1,0]
	v_pk_fma_f32 v[2:3], v[114:115], v[0:1], v[2:3] op_sel_hi:[1,0,1]
	v_pk_fma_f32 v[0:1], v[110:111], v[0:1], v[10:11] op_sel_hi:[1,0,1]
	global_store_dwordx4 v[158:159], v[0:3], off sc0 sc1
	global_load_dwordx4 v[8:11], v[160:161], off
	global_load_ushort v17, v[126:127], off offset:496
	v_fma_mix_f32 v5, v26, v109, v5 op_sel_hi:[0,1,0]
	v_fma_mix_f32 v5, v27, v109, v5 op_sel:[0,1,0] op_sel_hi:[0,1,0]
	v_mul_f32_e32 v1, v1, v99
	v_fma_mix_f32 v0, v0, v108, v1 op_sel_hi:[0,1,0]
	v_add_f32_dpp v5, v5, v5 quad_perm:[1,0,3,2] row_mask:0xf bank_mask:0xf bound_ctrl:1
	v_fma_mix_f32 v0, v2, v109, v0 op_sel_hi:[0,1,0]
	v_fma_mix_f32 v0, v3, v109, v0 op_sel:[0,1,0] op_sel_hi:[0,1,0]
	v_add_f32_dpp v5, v5, v5 quad_perm:[2,3,0,1] row_mask:0xf bank_mask:0xf bound_ctrl:1
	s_waitcnt vmcnt(1)
	v_pk_mul_f32 v[6:7], v[8:9], v[122:123]
	v_add_f32_dpp v5, v5, v5 row_ror:4 row_mask:0xf bank_mask:0xf bound_ctrl:1
	v_pk_mul_f32 v[12:13], v[10:11], v[124:125]
	v_add_f32_dpp v0, v0, v0 quad_perm:[1,0,3,2] row_mask:0xf bank_mask:0xf bound_ctrl:1
	v_add_f32_dpp v5, v5, v5 row_ror:8 row_mask:0xf bank_mask:0xf bound_ctrl:1
	v_fma_mix_f32 v5, v71, v83, v5 op_sel_hi:[0,1,0]
	v_cndmask_b32_e64 v4, v4, v5, s[14:15]
	v_mul_f32_e32 v5, v29, v99
	v_fma_mix_f32 v5, v28, v108, v5 op_sel_hi:[0,1,0]
	v_fma_mix_f32 v5, v30, v109, v5 op_sel_hi:[0,1,0]
	v_fma_mix_f32 v5, v31, v109, v5 op_sel:[0,1,0] op_sel_hi:[0,1,0]
	v_add_f32_dpp v0, v0, v0 quad_perm:[2,3,0,1] row_mask:0xf bank_mask:0xf bound_ctrl:1
	s_nop 0
	v_add_f32_dpp v5, v5, v5 quad_perm:[1,0,3,2] row_mask:0xf bank_mask:0xf bound_ctrl:1
	v_add_f32_dpp v0, v0, v0 row_ror:4 row_mask:0xf bank_mask:0xf bound_ctrl:1
	s_nop 0
	v_add_f32_dpp v5, v5, v5 quad_perm:[2,3,0,1] row_mask:0xf bank_mask:0xf bound_ctrl:1
	v_add_f32_dpp v0, v0, v0 row_ror:8 row_mask:0xf bank_mask:0xf bound_ctrl:1
	v_fma_mix_f32 v0, v71, v97, v0 op_sel_hi:[0,1,0]
	v_add_f32_dpp v5, v5, v5 row_ror:4 row_mask:0xf bank_mask:0xf bound_ctrl:1
	s_nop 1
	v_add_f32_dpp v5, v5, v5 row_ror:8 row_mask:0xf bank_mask:0xf bound_ctrl:1
	v_fma_mix_f32 v5, v71, v85, v5 op_sel_hi:[0,1,0]
	v_cndmask_b32_e64 v14, v4, v5, s[16:17]
	v_add_f32_e32 v5, v6, v7
	v_add_f32_e32 v5, v12, v5
	v_mul_f32_e32 v4, v33, v99
	v_add_f32_e32 v5, v13, v5
	v_fma_mix_f32 v4, v32, v108, v4 op_sel_hi:[0,1,0]
	v_fma_mix_f32 v4, v34, v109, v4 op_sel_hi:[0,1,0]
	v_add_f32_dpp v5, v5, v5 quad_perm:[1,0,3,2] row_mask:0xf bank_mask:0xf bound_ctrl:1
	v_fma_mix_f32 v15, v35, v109, v4 op_sel:[0,1,0] op_sel_hi:[0,1,0]
	s_waitcnt vmcnt(0)
	v_cvt_f32_f16_e32 v4, v17
	v_add_f32_dpp v5, v5, v5 quad_perm:[2,3,0,1] row_mask:0xf bank_mask:0xf bound_ctrl:1
	s_nop 1
	v_add_f32_dpp v5, v5, v5 row_ror:4 row_mask:0xf bank_mask:0xf bound_ctrl:1
	s_nop 1
	v_add_f32_dpp v6, v5, v5 row_ror:8 row_mask:0xf bank_mask:0xf bound_ctrl:1
	v_pk_mul_f32 v[12:13], v[116:117], v[6:7] op_sel_hi:[1,0]
	v_pk_mul_f32 v[6:7], v[112:113], v[6:7] op_sel_hi:[1,0]
	s_nop 0
	v_pk_fma_f32 v[8:9], v[118:119], v[8:9], v[6:7]
	v_pk_fma_f32 v[6:7], v[120:121], v[10:11], v[12:13]
	v_add_f32_dpp v13, v15, v15 quad_perm:[1,0,3,2] row_mask:0xf bank_mask:0xf bound_ctrl:1
	v_pk_fma_f32 v[6:7], v[114:115], v[4:5], v[6:7] op_sel_hi:[1,0,1]
	v_pk_fma_f32 v[4:5], v[110:111], v[4:5], v[8:9] op_sel_hi:[1,0,1]
	global_store_dwordx4 v[162:163], v[4:7], off sc0 sc1
	global_load_dwordx4 v[8:11], v[146:147], off
	global_load_ushort v12, v[150:151], off offset:384
	v_add_f32_dpp v13, v13, v13 quad_perm:[2,3,0,1] row_mask:0xf bank_mask:0xf bound_ctrl:1
	v_mul_f32_e32 v1, v5, v99
	v_fma_mix_f32 v1, v4, v108, v1 op_sel_hi:[0,1,0]
	v_add_f32_dpp v13, v13, v13 row_ror:4 row_mask:0xf bank_mask:0xf bound_ctrl:1
	v_fma_mix_f32 v1, v6, v109, v1 op_sel_hi:[0,1,0]
	v_fma_mix_f32 v1, v7, v109, v1 op_sel:[0,1,0] op_sel_hi:[0,1,0]
	v_add_f32_dpp v13, v13, v13 row_ror:8 row_mask:0xf bank_mask:0xf bound_ctrl:1
	v_fma_mix_f32 v13, v71, v87, v13 op_sel_hi:[0,1,0]
	v_cndmask_b32_e64 v13, v14, v13, s[18:19]
	v_mul_f32_e32 v14, v37, v99
	v_fma_mix_f32 v14, v36, v108, v14 op_sel_hi:[0,1,0]
	v_fma_mix_f32 v14, v38, v109, v14 op_sel_hi:[0,1,0]
	v_fma_mix_f32 v14, v39, v109, v14 op_sel:[0,1,0] op_sel_hi:[0,1,0]
	v_add_f32_dpp v1, v1, v1 quad_perm:[1,0,3,2] row_mask:0xf bank_mask:0xf bound_ctrl:1
	s_waitcnt vmcnt(1)
; __device__ __forceinline__ unsigned xb_add(unsigned* p, unsigned v) { return __hip_atomic_fetch_add(p, v, __ATOMIC_RELAXED, __HIP_MEMORY_SCOPE_AGENT); }
; __device__ __forceinline__ float row_sum16(float x) { x = dpp_add<0xB1>(x); x = dpp_add<0x4E>(x); x = dpp_add<0x124>(x); x = dpp_add<0x128>(x); return x; }
; __device__ __forceinline__ void xcd_barrier(const XB& b) {
;     __syncthreads();
;     if (threadIdx.x == 0) {
;         unsigned* bar = b.bar;
;         __builtin_amdgcn_fence(__ATOMIC_RELEASE, "agent");
;         asm volatile("s_waitcnt vmcnt(0)" ::: "memory");
;         const unsigned old = xb_add(&bar[XB_XSUB(b.x)], 1u);
;         const unsigned gen = old / b.nloc;
;         if (old + 1u == (gen + 1u) * b.nloc) {
;             const unsigned og = xb_add(&bar[XB_TOP], 1u);
; __device__ __forceinline__ void rwkv_sample_task(const Params& p, int s, int h) {
;     ...
;         S = S * d4 + sa * b4 + vv * k4;
;         float y = S[0] * r4[0] + S[1] * r4[1] + S[2] * r4[2] + S[3] * r4[3];
;         y = row_sum16(y) + rk * vv;
;         *(f32x4*)(So + (size_t)vrow * 64 + cg_ * 4) = S;
;         ysel = (cg_ == g) ? y : ysel;
;     }
;     const int vr = cg_ * 4 + rr, col = h * 64 + vr;
;     const float mu = wave_sum(ysel) * (1.f / 64.f);
;     const float dlt = ysel - mu;
;     const float rstd = rsqrtf(wave_sum(dlt * dlt) * (1.f / 64.f) + GN_EPS);
;     const float gte = (float)((const h16*)((unsigned char*)p.out + OUTB_G16))[(size_t)row * 512 + col];
;     ((h16*)((unsigned char*)p.out + OUTB_MIX16))[(size_t)row * D + 512 + col] = (h16)((dlt * rstd * p.in[24][col] + p.in[25][col]) * gte);
	v_pk_mul_f32 v[2:3], v[8:9], v[122:123]
	v_add_f32_dpp v14, v14, v14 quad_perm:[1,0,3,2] row_mask:0xf bank_mask:0xf bound_ctrl:1
	v_add_f32_dpp v1, v1, v1 quad_perm:[2,3,0,1] row_mask:0xf bank_mask:0xf bound_ctrl:1
	v_pk_mul_f32 v[4:5], v[10:11], v[124:125]
	v_add_f32_dpp v14, v14, v14 quad_perm:[2,3,0,1] row_mask:0xf bank_mask:0xf bound_ctrl:1
	v_add_f32_dpp v1, v1, v1 row_ror:4 row_mask:0xf bank_mask:0xf bound_ctrl:1
	s_nop 0
	v_add_f32_dpp v14, v14, v14 row_ror:4 row_mask:0xf bank_mask:0xf bound_ctrl:1
	v_add_f32_dpp v1, v1, v1 row_ror:8 row_mask:0xf bank_mask:0xf bound_ctrl:1
	v_fma_mix_f32 v1, v71, v17, v1 op_sel_hi:[0,1,0]
	v_add_f32_dpp v14, v14, v14 row_ror:8 row_mask:0xf bank_mask:0xf bound_ctrl:1
	v_fma_mix_f32 v14, v71, v89, v14 op_sel_hi:[0,1,0]
	v_cndmask_b32_e64 v13, v13, v14, s[20:21]
	v_mul_f32_e32 v14, v41, v99
	v_fma_mix_f32 v14, v40, v108, v14 op_sel_hi:[0,1,0]
	v_fma_mix_f32 v14, v42, v109, v14 op_sel_hi:[0,1,0]
	v_fma_mix_f32 v14, v43, v109, v14 op_sel:[0,1,0] op_sel_hi:[0,1,0]
	s_nop 1
	v_add_f32_dpp v14, v14, v14 quad_perm:[1,0,3,2] row_mask:0xf bank_mask:0xf bound_ctrl:1
	s_nop 1
	v_add_f32_dpp v14, v14, v14 quad_perm:[2,3,0,1] row_mask:0xf bank_mask:0xf bound_ctrl:1
	s_nop 1
	v_add_f32_dpp v14, v14, v14 row_ror:4 row_mask:0xf bank_mask:0xf bound_ctrl:1
	s_nop 1
	v_add_f32_dpp v14, v14, v14 row_ror:8 row_mask:0xf bank_mask:0xf bound_ctrl:1
	v_fma_mix_f32 v14, v71, v91, v14 op_sel_hi:[0,1,0]
	v_cndmask_b32_e64 v13, v13, v14, s[22:23]
	v_mul_f32_e32 v14, v45, v99
	v_fma_mix_f32 v14, v44, v108, v14 op_sel_hi:[0,1,0]
	v_fma_mix_f32 v14, v46, v109, v14 op_sel_hi:[0,1,0]
	v_fma_mix_f32 v14, v47, v109, v14 op_sel:[0,1,0] op_sel_hi:[0,1,0]
	s_nop 1
	v_add_f32_dpp v14, v14, v14 quad_perm:[1,0,3,2] row_mask:0xf bank_mask:0xf bound_ctrl:1
	s_nop 1
	v_add_f32_dpp v14, v14, v14 quad_perm:[2,3,0,1] row_mask:0xf bank_mask:0xf bound_ctrl:1
	s_nop 1
	v_add_f32_dpp v14, v14, v14 row_ror:4 row_mask:0xf bank_mask:0xf bound_ctrl:1
	s_nop 1
	v_add_f32_dpp v14, v14, v14 row_ror:8 row_mask:0xf bank_mask:0xf bound_ctrl:1
	v_fma_mix_f32 v14, v71, v93, v14 op_sel_hi:[0,1,0]
	v_cndmask_b32_e64 v13, v13, v14, s[24:25]
	v_mul_f32_e32 v14, v49, v99
	v_fma_mix_f32 v14, v48, v108, v14 op_sel_hi:[0,1,0]
	v_fma_mix_f32 v14, v50, v109, v14 op_sel_hi:[0,1,0]
	v_fma_mix_f32 v14, v51, v109, v14 op_sel:[0,1,0] op_sel_hi:[0,1,0]
	s_nop 1
	v_add_f32_dpp v14, v14, v14 quad_perm:[1,0,3,2] row_mask:0xf bank_mask:0xf bound_ctrl:1
	s_nop 1
	v_add_f32_dpp v14, v14, v14 quad_perm:[2,3,0,1] row_mask:0xf bank_mask:0xf bound_ctrl:1
	s_nop 1
	v_add_f32_dpp v14, v14, v14 row_ror:4 row_mask:0xf bank_mask:0xf bound_ctrl:1
	s_nop 1
	v_add_f32_dpp v14, v14, v14 row_ror:8 row_mask:0xf bank_mask:0xf bound_ctrl:1
	v_fma_mix_f32 v14, v71, v95, v14 op_sel_hi:[0,1,0]
	v_cndmask_b32_e64 v13, v13, v14, s[26:27]
	v_cndmask_b32_e64 v0, v13, v0, s[28:29]
	v_cndmask_b32_e64 v13, v0, v1, s[30:31]
	v_add_f32_e32 v1, v2, v3
	v_add_f32_e32 v1, v4, v1
	v_add_f32_e32 v1, v5, v1
	s_waitcnt vmcnt(0)
	v_cvt_f32_f16_e32 v0, v12
	v_add_f32_dpp v1, v1, v1 quad_perm:[1,0,3,2] row_mask:0xf bank_mask:0xf bound_ctrl:1
	s_nop 1
	v_add_f32_dpp v1, v1, v1 quad_perm:[2,3,0,1] row_mask:0xf bank_mask:0xf bound_ctrl:1
	s_nop 1
	v_add_f32_dpp v1, v1, v1 row_ror:4 row_mask:0xf bank_mask:0xf bound_ctrl:1
	s_nop 1
	v_add_f32_dpp v2, v1, v1 row_ror:8 row_mask:0xf bank_mask:0xf bound_ctrl:1
	v_pk_mul_f32 v[4:5], v[116:117], v[2:3] op_sel_hi:[1,0]
	v_pk_mul_f32 v[2:3], v[112:113], v[2:3] op_sel_hi:[1,0]
	s_nop 0
	v_pk_fma_f32 v[6:7], v[118:119], v[8:9], v[2:3]
	v_pk_fma_f32 v[2:3], v[120:121], v[10:11], v[4:5]
	s_nop 0
	v_pk_fma_f32 v[2:3], v[114:115], v[0:1], v[2:3] op_sel_hi:[1,0,1]
	v_pk_fma_f32 v[0:1], v[110:111], v[0:1], v[6:7] op_sel_hi:[1,0,1]
	global_store_dwordx4 v[148:149], v[0:3], off sc0 sc1
	v_mul_f32_e32 v4, v1, v99
	s_nop 0
	v_fma_mix_f32 v0, v0, v108, v4 op_sel_hi:[0,1,0]
	v_fma_mix_f32 v0, v2, v109, v0 op_sel_hi:[0,1,0]
	v_fma_mix_f32 v0, v3, v109, v0 op_sel:[0,1,0] op_sel_hi:[0,1,0]
	global_load_ushort v3, v[156:157], off
	global_load_dword v4, v[66:67], off
	global_load_dword v5, v[68:69], off
	v_add_f32_dpp v0, v0, v0 quad_perm:[1,0,3,2] row_mask:0xf bank_mask:0xf bound_ctrl:1
	s_nop 1
	v_add_f32_dpp v0, v0, v0 quad_perm:[2,3,0,1] row_mask:0xf bank_mask:0xf bound_ctrl:1
	s_nop 1
	v_add_f32_dpp v0, v0, v0 row_ror:4 row_mask:0xf bank_mask:0xf bound_ctrl:1
	s_nop 1
	v_add_f32_dpp v0, v0, v0 row_ror:8 row_mask:0xf bank_mask:0xf bound_ctrl:1
	v_fma_mix_f32 v0, v71, v12, v0 op_sel_hi:[0,1,0]
	v_cndmask_b32_e64 v2, v13, v0, s[34:35]
	ds_bpermute_b32 v0, v55, v2
	s_waitcnt lgkmcnt(0)
	v_add_f32_e32 v0, v2, v0
	ds_bpermute_b32 v1, v57, v0
	s_waitcnt lgkmcnt(0)
	v_add_f32_e32 v0, v0, v1
	ds_bpermute_b32 v1, v129, v0
	s_waitcnt lgkmcnt(0)
	v_add_f32_e32 v0, v0, v1
	ds_bpermute_b32 v1, v135, v0
	s_waitcnt lgkmcnt(0)
	v_add_f32_e32 v0, v0, v1
	ds_bpermute_b32 v1, v137, v0
	s_waitcnt lgkmcnt(0)
	v_add_f32_e32 v0, v0, v1
	ds_bpermute_b32 v1, v139, v0
	s_waitcnt lgkmcnt(0)
	v_add_f32_e32 v0, v0, v1
	v_fmac_f32_e32 v2, 0xbc800000, v0
	v_mul_f32_e32 v0, v2, v2
	ds_bpermute_b32 v0, v55, v0
	s_waitcnt lgkmcnt(0)
	v_fmac_f32_e32 v0, v2, v2
	ds_bpermute_b32 v1, v57, v0
	s_waitcnt lgkmcnt(0)
	v_add_f32_e32 v0, v0, v1
	ds_bpermute_b32 v1, v129, v0
	s_waitcnt lgkmcnt(0)
	v_add_f32_e32 v0, v0, v1
	ds_bpermute_b32 v1, v135, v0
	s_waitcnt lgkmcnt(0)
	v_add_f32_e32 v0, v0, v1
	ds_bpermute_b32 v1, v137, v0
	s_waitcnt lgkmcnt(0)
	v_add_f32_e32 v0, v0, v1
	ds_bpermute_b32 v1, v139, v0
	s_waitcnt lgkmcnt(0)
	v_add_f32_e32 v0, v0, v1
	v_fmamk_f32 v0, v0, 0x3c800000, v141
	v_mul_f32_e32 v1, 0x4b800000, v0
	v_cmp_gt_f32_e64 s[36:37], s44, v0
	s_nop 1
	v_cndmask_b32_e64 v0, v0, v1, s[36:37]
	v_rsq_f32_e32 v6, v0
	v_lshlrev_b64 v[0:1], 11, v[106:107]
	v_lshl_add_u64 v[0:1], v[62:63], 0, v[0:1]
	v_mul_f32_e32 v7, 0x45800000, v6
	v_cndmask_b32_e64 v6, v6, v7, s[36:37]
	v_mul_f32_e32 v2, v2, v6
	s_waitcnt vmcnt(0)
	v_fmac_f32_e32 v5, v4, v2
	v_fma_mixlo_f16 v2, v5, v3, 0 op_sel_hi:[0,1,0]
	global_store_short v[0:1], v2, off offset:1024 sc0 sc1
	s_andn2_b64 exec, exec, s[42:43]
	s_cbranch_execnz .LBB0_362
.LBB0_363:
	s_or_b64 exec, exec, s[38:39]
	s_waitcnt vmcnt(0)
	s_barrier
	s_mov_b64 s[0:1], exec
	v_readlane_b32 s4, v253, 2
	v_readlane_b32 s5, v253, 3
	s_and_b64 s[4:5], s[0:1], s[4:5]
	s_mov_b64 exec, s[4:5]
	s_cbranch_execz .LBB0_382
	s_mov_b64 s[6:7], exec
	s_nop 0
	s_waitcnt vmcnt(0)
	s_waitcnt vmcnt(0)
	s_lshl_b32 s3, s89, 8
	v_readlane_b32 s4, v253, 0
	v_mbcnt_lo_u32_b32 v0, s6, 0
	v_readlane_b32 s5, v253, 1
	s_add_u32 s4, s4, s3
	v_mbcnt_hi_u32_b32 v0, s7, v0
	s_addc_u32 s5, s5, 0
	v_cmp_eq_u32_e32 vcc, 0, v0
	s_and_saveexec_b64 s[8:9], vcc
	s_cbranch_execz .LBB0_366
	s_bcnt1_i32_b64 s3, s[6:7]
	v_mov_b32_e32 v1, 0x1000
	v_mov_b32_e32 v2, s3
	global_atomic_add v1, v1, v2, s[4:5] sc0

; __device__ __forceinline__ f32x4 mfma16(h16x8 a, h16x8 b, f32x4 c) { return __builtin_amdgcn_mfma_f32_16x16x32_f16(a, b, c, 0, 0, 0); }
; __device__ __forceinline__ unsigned xb_add(unsigned* p, unsigned v) { return __hip_atomic_fetch_add(p, v, __ATOMIC_RELAXED, __HIP_MEMORY_SCOPE_AGENT); }
; __device__ __forceinline__ void xcd_barrier(const XB& b) {
;     __syncthreads();
;     if (threadIdx.x == 0) {
;         unsigned* bar = b.bar;
;         __builtin_amdgcn_fence(__ATOMIC_RELEASE, "agent");
;         asm volatile("s_waitcnt vmcnt(0)" ::: "memory");
;         const unsigned old = xb_add(&bar[XB_XSUB(b.x)], 1u);
;         const unsigned gen = old / b.nloc;
;         if (old + 1u == (gen + 1u) * b.nloc) {
;             const unsigned og = xb_add(&bar[XB_TOP], 1u);
; template <int MODE>
; __device__ __forceinline__ void skinny(const Params& p, const h16* A, int lda, int row0, int nrt, const h16* Bt, int K, int nct) {
;     ...
;     for (int task = gw; task < nrt * nct; task += ngw) {
;         const int rt = task % nrt, ct = task / nrt;
;         const h16* ap = A + (size_t)(row0 + rt * 16 + fr) * lda + fq * 8;
;         const h16* bp = Bt + (size_t)(ct * 16 + fr) * K + fq * 8;
;         f32x4 acc = {0.f, 0.f, 0.f, 0.f};
; #pragma unroll 8
;         for (int k = 0; k < K; k += 32) { const h16x8 a = *(const h16x8*)(ap + k); const h16x8 b = *(const h16x8*)(bp + k); acc = mfma16(b, a, acc); }
;         const int row = row0 + rt * 16 + fr, col = ct * 16 + fq * 4;
;         if (MODE == SK_GATES) {
;             const float* bi = p.in[12]; const float* bf = p.in[13];
;             f32x4 o;
; #pragma unroll
;             for (int r = 0; r < 4; ++r) { const int cc = col + r; o[r] = acc[r] + (cc < 8 ? bi[cc] : bf[cc - 8]); }
;             *(f32x4*)((float*)(ws + OFF_GATES) + (size_t)row * 16 + col) = o;
;         } else if (MODE == SK_OUT) {
;             const int s = row - MP;
;             f32x4 v = acc + *(const f32x4*)(p.in[1] + (size_t)s * D + col);
;             *(f32x4*)((float*)(ws + OFF_X1) + (size_t)row * D + col) = v;
;             *(h16x4*)((h16*)(ws + OFF_X116) + (size_t)row * D + col) = pack4(v);
;             float ss = v[0] * v[0] + v[1] * v[1] + v[2] * v[2] + v[3] * v[3];
;             ss += __shfl_xor(ss, 16); ss += __shfl_xor(ss, 32);
;             if (fq == 0) atomicAdd((float*)(ws + OFF_SS1) + row, ss);
.LBB0_446:
	v_lshl_add_u64 v[36:37], v[8:9], 0, v[140:141]
	v_add_co_u32_e32 v54, vcc, 0x788000, v36
	v_lshl_add_u64 v[52:53], v[10:11], 0, v[140:141]
	s_nop 0
	v_addc_co_u32_e32 v55, vcc, 0, v37, vcc
	global_load_dwordx4 v[16:19], v[52:53], off
	global_load_dwordx4 v[20:23], v[52:53], off offset:64
	global_load_dwordx4 v[24:27], v[52:53], off offset:128
	global_load_dwordx4 v[28:31], v[52:53], off offset:192
	global_load_dwordx4 v[32:35], v[52:53], off offset:256
	global_load_dwordx4 v[36:39], v[54:55], off
	global_load_dwordx4 v[40:43], v[54:55], off offset:64
	global_load_dwordx4 v[44:47], v[54:55], off offset:128
	global_load_dwordx4 v[48:51], v[54:55], off offset:192
	s_addk_i32 s16, 0x100
	v_lshl_add_u64 v[8:9], v[8:9], 0, s[12:13]
	s_cmpk_gt_u32 s16, 0x3df
	v_lshl_add_u64 v[10:11], v[10:11], 0, s[12:13]
	s_waitcnt vmcnt(3)
	v_mfma_f32_16x16x32_f16 v[0:3], v[36:39], v[16:19], v[0:3]
	global_load_dwordx4 v[16:19], v[54:55], off offset:256
	s_waitcnt vmcnt(3)
	v_mfma_f32_16x16x32_f16 v[0:3], v[40:43], v[20:23], v[0:3]
	global_load_dwordx4 v[20:23], v[54:55], off offset:320
	s_waitcnt vmcnt(3)
	v_mfma_f32_16x16x32_f16 v[0:3], v[44:47], v[24:27], v[0:3]
	global_load_dwordx4 v[24:27], v[52:53], off offset:320
	s_waitcnt vmcnt(3)
	v_mfma_f32_16x16x32_f16 v[0:3], v[48:51], v[28:31], v[0:3]
	global_load_dwordx4 v[28:31], v[54:55], off offset:384
	global_load_dwordx4 v[36:39], v[52:53], off offset:384
	s_waitcnt vmcnt(4)
	v_mfma_f32_16x16x32_f16 v[0:3], v[16:19], v[32:35], v[0:3]
	global_load_dwordx4 v[16:19], v[54:55], off offset:448
	s_waitcnt vmcnt(3)
	v_mfma_f32_16x16x32_f16 v[0:3], v[20:23], v[24:27], v[0:3]
	global_load_dwordx4 v[20:23], v[52:53], off offset:448
	s_waitcnt vmcnt(2)
	v_mfma_f32_16x16x32_f16 v[0:3], v[28:31], v[36:39], v[0:3]
	s_waitcnt vmcnt(0)
	v_mfma_f32_16x16x32_f16 v[0:3], v[16:19], v[20:23], v[0:3]
	s_cbranch_scc0 .LBB0_446
	v_or_b32_e32 v16, v15, v138
	v_ashrrev_i32_e32 v9, 31, v4
	v_mov_b32_e32 v8, v4
	v_readlane_b32 s44, v253, 4
	v_lshlrev_b64 v[8:9], 12, v[8:9]
	v_readlane_b32 s46, v253, 6
	v_readlane_b32 s47, v253, 7
	v_ashrrev_i32_e32 v17, 31, v16
	v_lshlrev_b64 v[18:19], 2, v[16:17]
	v_lshl_add_u64 v[8:9], s[46:47], 0, v[8:9]
	v_lshl_add_u64 v[8:9], v[8:9], 0, v[18:19]
	v_add_co_u32_e32 v8, vcc, 0xfc000000, v8
	v_lshl_add_u64 v[6:7], s[10:11], 0, v[6:7]
	s_nop 0
	v_addc_co_u32_e32 v9, vcc, -1, v9, vcc
	global_load_dwordx4 v[8:11], v[8:9], off
	v_lshl_add_u64 v[6:7], v[16:17], 1, v[6:7]
	v_readlane_b32 s45, v253, 5
	v_readlane_b32 s48, v253, 8
	v_readlane_b32 s49, v253, 9
	v_readlane_b32 s50, v253, 10
	v_readlane_b32 s51, v253, 11
	v_readlane_b32 s52, v253, 12
	v_readlane_b32 s53, v253, 13
	v_readlane_b32 s54, v253, 14
	v_readlane_b32 s55, v253, 15
	v_readlane_b32 s56, v253, 16
	v_readlane_b32 s57, v253, 17
	v_readlane_b32 s58, v253, 18
	v_readlane_b32 s59, v253, 19
	s_waitcnt vmcnt(0)
	v_pk_add_f32 v[8:9], v[0:1], v[8:9]
	v_pk_add_f32 v[10:11], v[2:3], v[10:11]
	v_mul_f32_e32 v2, v9, v9
	v_fmac_f32_e32 v2, v8, v8
	v_fmac_f32_e32 v2, v10, v10
	v_fmac_f32_e32 v2, v11, v11
	ds_bpermute_b32 v15, v12, v2
	v_lshlrev_b64 v[0:1], 12, v[4:5]
	v_lshl_add_u64 v[0:1], s[86:87], 0, v[0:1]
	v_lshl_add_u64 v[0:1], v[0:1], 0, v[18:19]
	global_store_dwordx4 v[0:1], v[8:11], off sc0 sc1
	s_waitcnt lgkmcnt(0)
	v_add_f32_e32 v0, v2, v15
	ds_bpermute_b32 v1, v13, v0
	v_cvt_pk_f16_f32 v3, v10, v11
	v_cvt_pk_f16_f32 v2, v8, v9
	global_store_dwordx2 v[6:7], v[2:3], off sc0 sc1
	s_and_saveexec_b64 s[16:17], s[6:7]
	s_cbranch_execz .LBB0_444
	s_waitcnt lgkmcnt(0)
	v_add_f32_e32 v2, v0, v1
	v_lshl_add_u64 v[0:1], v[4:5], 2, s[14:15]
	global_atomic_add_f32 v[0:1], v2, off
	s_branch .LBB0_444
.LBB0_449:
	s_or_b64 exec, exec, s[0:1]
	s_waitcnt lgkmcnt(0)
	s_waitcnt vmcnt(0)
	s_barrier
	s_mov_b64 s[0:1], exec
	v_readlane_b32 s6, v253, 2
	v_readlane_b32 s7, v253, 3
	s_and_b64 s[6:7], s[0:1], s[6:7]
	s_mov_b64 exec, s[6:7]
	s_cbranch_execz .LBB0_468
	s_mov_b64 s[8:9], exec
	s_nop 0
	s_waitcnt vmcnt(0)
	s_waitcnt vmcnt(0)
	s_lshl_b32 s6, s89, 8
	v_readlane_b32 s12, v253, 0
	v_mbcnt_lo_u32_b32 v0, s8, 0
	v_readlane_b32 s13, v253, 1
	s_add_u32 s6, s12, s6
	v_mbcnt_hi_u32_b32 v0, s9, v0
	s_addc_u32 s7, s13, 0
	v_cmp_eq_u32_e32 vcc, 0, v0
	s_and_saveexec_b64 s[12:13], vcc
	s_cbranch_execz .LBB0_452
	s_bcnt1_i32_b64 s8, s[8:9]
	v_mov_b32_e32 v1, 0x1000
	v_mov_b32_e32 v2, s8
	global_atomic_add v1, v1, v2, s[6:7] sc0

; __device__ __forceinline__ unsigned xb_add(unsigned* p, unsigned v) { return __hip_atomic_fetch_add(p, v, __ATOMIC_RELAXED, __HIP_MEMORY_SCOPE_AGENT); }
; __device__ __forceinline__ void xcd_barrier(const XB& b) {
;     __syncthreads();
;     if (threadIdx.x == 0) {
;         unsigned* bar = b.bar;
;         __builtin_amdgcn_fence(__ATOMIC_RELEASE, "agent");
;         asm volatile("s_waitcnt vmcnt(0)" ::: "memory");
;         const unsigned old = xb_add(&bar[XB_XSUB(b.x)], 1u);
;         const unsigned gen = old / b.nloc;
;         if (old + 1u == (gen + 1u) * b.nloc) {
;             const unsigned og = xb_add(&bar[XB_TOP], 1u);
; template <int MODE>
; __device__ __forceinline__ void skinny(const Params& p, const h16* A, int lda, int row0, int nrt, const h16* Bt, int K, int nct) {
;     ...
;         } else if (MODE == SK_UP) {
;             const float rstd = rsqrtf(((const float*)(ws + OFF_SS1))[row] * (1.f / 1024.f) + EPS);
;             f32x4 v;
; #pragma unroll
;             for (int r = 0; r < 4; ++r) { const float a = fmaxf(acc[r] * rstd, 0.f); v[r] = a * a; }
;             *(h16x4*)((h16*)(ws + OFF_HID16) + (size_t)row * DFF + col) = pack4(v);
.Lsk5_done:
	v_lshl_add_u64 v[6:7], v[4:5], 2, s[14:15]
	global_load_dword v7, v[6:7], off
	v_lshlrev_b64 v[8:9], 13, v[4:5]
	v_or_b32_e32 v6, v12, v138
	v_lshl_add_u64 v[8:9], s[12:13], 0, v[8:9]
	v_add_u32_e32 v11, s88, v11
	v_cmp_lt_i32_e64 s[0:1], s19, v11
	s_or_b64 s[8:9], s[0:1], s[8:9]
	s_waitcnt vmcnt(0)
	v_fmamk_f32 v4, v7, 0x3a800000, v10
	v_mul_f32_e32 v7, 0x4b800000, v4
	v_cmp_gt_f32_e32 vcc, s18, v4
	s_nop 1
	v_cndmask_b32_e32 v4, v4, v7, vcc
	v_rsq_f32_e32 v4, v4
	v_ashrrev_i32_e32 v7, 31, v6
	v_lshl_add_u64 v[6:7], v[6:7], 1, v[8:9]
	v_mul_f32_e32 v8, 0x45800000, v4
	v_cndmask_b32_e32 v4, v4, v8, vcc
	v_mul_f32_e32 v0, v0, v4
	v_mul_f32_e32 v1, v1, v4
	v_mul_f32_e32 v2, v2, v4
	v_mul_f32_e32 v3, v3, v4
	v_max_f32_e32 v4, 0, v0
	v_max_f32_e32 v0, 0, v1
	v_max_f32_e32 v1, 0, v2
	v_max_f32_e32 v2, 0, v3
	v_pk_mul_f32 v[0:1], v[0:1], v[0:1]
	v_fma_mixlo_f16 v3, v4, v4, 0
	v_fma_mixlo_f16 v2, v2, v2, 0
	v_cvt_pk_f16_f32 v1, v0, v1
	v_pack_b32_f16 v0, v3, v1
	v_alignbit_b32 v1, v2, v1, 16
	global_store_dwordx2 v[6:7], v[0:1], off sc0 sc1
	s_andn2_b64 exec, exec, s[8:9]
	s_cbranch_execnz .LBB0_490
.LBB0_493:
	s_or_b64 exec, exec, s[6:7]
	s_waitcnt lgkmcnt(0)
	s_waitcnt vmcnt(0)
	s_barrier
	s_mov_b64 s[0:1], exec
	v_readlane_b32 s6, v253, 2
	v_readlane_b32 s7, v253, 3
	s_and_b64 s[6:7], s[0:1], s[6:7]
	s_mov_b64 exec, s[6:7]
	s_cbranch_execz .LBB0_512
	s_mov_b64 s[8:9], exec
	s_nop 0
	s_waitcnt vmcnt(0)
	s_waitcnt vmcnt(0)
	s_lshl_b32 s6, s89, 8
	v_readlane_b32 s14, v253, 0
	v_mbcnt_lo_u32_b32 v0, s8, 0
	v_readlane_b32 s15, v253, 1
	s_add_u32 s6, s14, s6
	v_mbcnt_hi_u32_b32 v0, s9, v0
	s_addc_u32 s7, s15, 0
	v_cmp_eq_u32_e32 vcc, 0, v0
	s_and_saveexec_b64 s[14:15], vcc
	s_cbranch_execz .LBB0_496
	s_bcnt1_i32_b64 s8, s[8:9]
	v_mov_b32_e32 v1, 0x1000
	v_mov_b32_e32 v2, s8
	global_atomic_add v1, v1, v2, s[6:7] sc0

; #define PG8_STAGE(bufoff, gbase, voff) do { _Pragma("unroll") for (int _i = 0; _i < 2; ++_i) \
;         __builtin_amdgcn_global_load_lds((const unsigned*)((const char*)(gbase) + (voff)[_i]), (LAS unsigned*)(lds + (bufoff) + ldsw + _i * 8192), 16, 0, 0); } while (0)
; #define PG8_LDA(dst, b, h) do { _Pragma("unroll") for (int m = 0; m < 4; ++m) _Pragma("unroll") for (int k = 0; k < 2; ++k) dst[m][k] = *(const LAS h16x8*)(lds + PG8_SA(b, h) + aoff + m * 2048 + k * 1024); } while (0)
; #define PG8_LDB(dst, b, h) do { _Pragma("unroll") for (int n = 0; n < 2; ++n) _Pragma("unroll") for (int k = 0; k < 2; ++k) dst[n][k] = *(const LAS h16x8*)(lds + PG8_SB(b, h) + boff + n * 2048 + k * 1024); } while (0)
; #define PG8_MMA(ai, bj, At, Bt) do { __builtin_amdgcn_s_setprio(1); _Pragma("unroll") for (int m = 0; m < 4; ++m) _Pragma("unroll") for (int n = 0; n < 2; ++n) _Pragma("unroll") for (int k = 0; k < 2; ++k) \
;         acc[ai][bj][m][n] = __builtin_amdgcn_mfma_f32_16x16x32_f16(Bt[n][k], At[m][k], acc[ai][bj][m][n], 0, 0, 0); __builtin_amdgcn_s_setprio(0); } while (0)
; #define PG8_WAIT_V(n) asm volatile("s_waitcnt vmcnt(" #n ")" ::: "memory")
; #define PG8_WAIT_L(n) asm volatile("s_waitcnt lgkmcnt(" #n ")" ::: "memory")
; #define PG8_BAR __builtin_amdgcn_s_barrier()
; #define PG8_SCHED __builtin_amdgcn_sched_barrier(0)
; template <class Epi>
; __device__ __forceinline__ void gemm_phase(LAS unsigned char* lds, const Gemm g, const StaticOrder& S, const Epi& E) {
;     ...
;             PG8_LDB(B0, 0, 0); PG8_SCHED; PG8_LDA(At, 0, 0); PG8_STAGE(PG8_SA(1, 1), a1 + hstep, voffA);
;             PG8_WAIT_L(8); PG8_BAR; PG8_WAIT_L(0); PG8_MMA(0, 0, At, B0); PG8_BAR; PG8_SCHED;
;             PG8_LDB(B1, 0, 1); PG8_STAGE(PG8_SB(0, 0), b2, voffB);
;             PG8_BAR; PG8_WAIT_L(0); PG8_MMA(0, 1, At, B1); PG8_BAR;
;             PG8_LDA(At, 0, 1); PG8_STAGE(PG8_SA(0, 0), a2, voffA);
;             PG8_BAR; PG8_WAIT_L(0); PG8_MMA(1, 0, At, B0); PG8_BAR; PG8_SCHED;
;             PG8_STAGE(PG8_SB(0, 1), b2 + hstep, voffB);
;             PG8_WAIT_V(6); PG8_BAR; PG8_MMA(1, 1, At, B1); PG8_BAR;
;             PG8_LDB(B0, 1, 0); PG8_SCHED; PG8_LDA(At, 1, 0); PG8_STAGE(PG8_SA(0, 1), a2 + hstep, voffA);
;             PG8_WAIT_L(8); PG8_BAR; PG8_WAIT_L(0); PG8_MMA(0, 0, At, B0); PG8_BAR; PG8_SCHED;
.LBB0_531:
	ds_read_b128 v[156:159], v161
	ds_read_b128 v[164:167], v161 offset:1024
	ds_read_b128 v[168:171], v161 offset:2048
	ds_read_b128 v[172:175], v161 offset:3072
	s_add_u32 s34, s30, 0xfff00080
	s_addc_u32 s35, s31, -1
	s_cmp_eq_u32 s54, 60
	s_cselect_b32 s37, s21, s35
	s_cselect_b32 s36, s27, s34
	s_cselect_b32 s35, s19, s53
	s_cselect_b32 s34, s51, s52
	v_lshl_add_u64 v[208:209], s[30:31], 0, v[148:149]
	s_add_i32 m0, s29, 0xc000
	ds_read_b128 v[176:179], v162
	ds_read_b128 v[180:183], v162 offset:1024
	ds_read_b128 v[184:187], v162 offset:2048
	ds_read_b128 v[188:191], v162 offset:3072
	ds_read_b128 v[192:195], v162 offset:4096
	ds_read_b128 v[196:199], v162 offset:5120
	ds_read_b128 v[200:203], v162 offset:6144
	ds_read_b128 v[204:207], v162 offset:7168
	global_load_lds_dwordx4 v[208:209], off
	v_lshl_add_u64 v[208:209], s[30:31], 0, v[150:151]
	s_add_i32 m0, s29, 0xe000
	s_nop 0
	global_load_lds_dwordx4 v[208:209], off
	s_waitcnt lgkmcnt(8)
	s_barrier
	s_waitcnt lgkmcnt(0)
	s_setprio 1
	s_waitcnt lgkmcnt(0)
	v_mfma_f32_16x16x32_f16 v[124:127], v[156:159], v[176:179], v[124:127]
	v_mfma_f32_16x16x32_f16 v[120:123], v[168:171], v[176:179], v[120:123]
	v_mfma_f32_16x16x32_f16 v[108:111], v[156:159], v[184:187], v[108:111]
	v_mfma_f32_16x16x32_f16 v[104:107], v[168:171], v[184:187], v[104:107]
	v_mfma_f32_16x16x32_f16 v[92:95], v[156:159], v[192:195], v[92:95]
	v_mfma_f32_16x16x32_f16 v[88:91], v[168:171], v[192:195], v[88:91]
	v_mfma_f32_16x16x32_f16 v[76:79], v[156:159], v[200:203], v[76:79]
	v_mfma_f32_16x16x32_f16 v[72:75], v[168:171], v[200:203], v[72:75]
	v_mfma_f32_16x16x32_f16 v[124:127], v[164:167], v[180:183], v[124:127]
	v_mfma_f32_16x16x32_f16 v[120:123], v[172:175], v[180:183], v[120:123]
	v_mfma_f32_16x16x32_f16 v[108:111], v[164:167], v[188:191], v[108:111]
	v_mfma_f32_16x16x32_f16 v[104:107], v[172:175], v[188:191], v[104:107]
	v_mfma_f32_16x16x32_f16 v[92:95], v[164:167], v[196:199], v[92:95]
	v_mfma_f32_16x16x32_f16 v[88:91], v[172:175], v[196:199], v[88:91]
	v_mfma_f32_16x16x32_f16 v[76:79], v[164:167], v[204:207], v[76:79]
	v_mfma_f32_16x16x32_f16 v[72:75], v[172:175], v[204:207], v[72:75]
	s_setprio 0
	s_barrier
	s_add_i32 s55, s49, s42
	v_lshl_add_u64 v[224:225], s[34:35], 0, v[140:141]
	s_mov_b32 m0, s55
	ds_read_b128 v[208:211], v163
	ds_read_b128 v[212:215], v163 offset:1024
	ds_read_b128 v[216:219], v163 offset:2048
	ds_read_b128 v[220:223], v163 offset:3072
	global_load_lds_dwordx4 v[224:225], off
	v_lshl_add_u64 v[226:227], s[34:35], 0, v[144:145]
	s_add_i32 m0, s55, 0x2000
	s_nop 0
	global_load_lds_dwordx4 v[226:227], off
	s_barrier
	s_waitcnt lgkmcnt(0)
	s_setprio 1
	s_waitcnt lgkmcnt(0)
	v_mfma_f32_16x16x32_f16 v[116:119], v[208:211], v[176:179], v[116:119]
	v_mfma_f32_16x16x32_f16 v[112:115], v[216:219], v[176:179], v[112:115]
	v_mfma_f32_16x16x32_f16 v[100:103], v[208:211], v[184:187], v[100:103]
	v_mfma_f32_16x16x32_f16 v[96:99], v[216:219], v[184:187], v[96:99]
	v_mfma_f32_16x16x32_f16 v[84:87], v[208:211], v[192:195], v[84:87]
	v_mfma_f32_16x16x32_f16 v[80:83], v[216:219], v[192:195], v[80:83]
	v_mfma_f32_16x16x32_f16 v[68:71], v[208:211], v[200:203], v[68:71]
	v_mfma_f32_16x16x32_f16 v[64:67], v[216:219], v[200:203], v[64:67]
	v_mfma_f32_16x16x32_f16 v[116:119], v[212:215], v[180:183], v[116:119]
	v_mfma_f32_16x16x32_f16 v[112:115], v[220:223], v[180:183], v[112:115]
	v_mfma_f32_16x16x32_f16 v[100:103], v[212:215], v[188:191], v[100:103]
	v_mfma_f32_16x16x32_f16 v[96:99], v[220:223], v[188:191], v[96:99]
	v_mfma_f32_16x16x32_f16 v[84:87], v[212:215], v[196:199], v[84:87]
	v_mfma_f32_16x16x32_f16 v[80:83], v[220:223], v[196:199], v[80:83]
	v_mfma_f32_16x16x32_f16 v[68:71], v[212:215], v[204:207], v[68:71]
	v_mfma_f32_16x16x32_f16 v[64:67], v[220:223], v[204:207], v[64:67]
	s_setprio 0
	s_mov_b32 m0, s29
	v_lshl_add_u64 v[228:229], s[36:37], 0, v[138:139]
	s_barrier
	ds_read_b128 v[176:179], v162 offset:16384
	ds_read_b128 v[180:183], v162 offset:17408
	ds_read_b128 v[184:187], v162 offset:18432
	ds_read_b128 v[188:191], v162 offset:19456
	ds_read_b128 v[192:195], v162 offset:20480
	ds_read_b128 v[196:199], v162 offset:21504
	ds_read_b128 v[200:203], v162 offset:22528
	ds_read_b128 v[204:207], v162 offset:23552
	global_load_lds_dwordx4 v[228:229], off
	v_lshl_add_u64 v[230:231], s[36:37], 0, v[142:143]
	s_mov_b32 m0, s43
	s_nop 0
	global_load_lds_dwordx4 v[230:231], off
	s_barrier
	s_waitcnt lgkmcnt(0)
	s_setprio 1
	s_waitcnt lgkmcnt(0)
	v_mfma_f32_16x16x32_f16 v[60:63], v[156:159], v[176:179], v[60:63]
	v_mfma_f32_16x16x32_f16 v[56:59], v[168:171], v[176:179], v[56:59]
	v_mfma_f32_16x16x32_f16 v[44:47], v[156:159], v[184:187], v[44:47]
	v_mfma_f32_16x16x32_f16 v[40:43], v[168:171], v[184:187], v[40:43]
	v_mfma_f32_16x16x32_f16 v[28:31], v[156:159], v[192:195], v[28:31]
	v_mfma_f32_16x16x32_f16 v[24:27], v[168:171], v[192:195], v[24:27]
	v_mfma_f32_16x16x32_f16 v[12:15], v[156:159], v[200:203], v[12:15]
	v_mfma_f32_16x16x32_f16 v[8:11], v[168:171], v[200:203], v[8:11]
	v_mfma_f32_16x16x32_f16 v[60:63], v[164:167], v[180:183], v[60:63]
	v_mfma_f32_16x16x32_f16 v[56:59], v[172:175], v[180:183], v[56:59]
	v_mfma_f32_16x16x32_f16 v[44:47], v[164:167], v[188:191], v[44:47]
	v_mfma_f32_16x16x32_f16 v[40:43], v[172:175], v[188:191], v[40:43]
	v_mfma_f32_16x16x32_f16 v[28:31], v[164:167], v[196:199], v[28:31]
	v_mfma_f32_16x16x32_f16 v[24:27], v[172:175], v[196:199], v[24:27]
	v_mfma_f32_16x16x32_f16 v[12:15], v[164:167], v[204:207], v[12:15]
	v_mfma_f32_16x16x32_f16 v[8:11], v[172:175], v[204:207], v[8:11]
	s_setprio 0
	s_barrier
; #define PG8_STAGE(bufoff, gbase, voff) do { _Pragma("unroll") for (int _i = 0; _i < 2; ++_i) \
;         __builtin_amdgcn_global_load_lds((const unsigned*)((const char*)(gbase) + (voff)[_i]), (LAS unsigned*)(lds + (bufoff) + ldsw + _i * 8192), 16, 0, 0); } while (0)
; #define PG8_LDA(dst, b, h) do { _Pragma("unroll") for (int m = 0; m < 4; ++m) _Pragma("unroll") for (int k = 0; k < 2; ++k) dst[m][k] = *(const LAS h16x8*)(lds + PG8_SA(b, h) + aoff + m * 2048 + k * 1024); } while (0)
; #define PG8_LDB(dst, b, h) do { _Pragma("unroll") for (int n = 0; n < 2; ++n) _Pragma("unroll") for (int k = 0; k < 2; ++k) dst[n][k] = *(const LAS h16x8*)(lds + PG8_SB(b, h) + boff + n * 2048 + k * 1024); } while (0)
; #define PG8_MMA(ai, bj, At, Bt) do { __builtin_amdgcn_s_setprio(1); _Pragma("unroll") for (int m = 0; m < 4; ++m) _Pragma("unroll") for (int n = 0; n < 2; ++n) _Pragma("unroll") for (int k = 0; k < 2; ++k) \
;         acc[ai][bj][m][n] = __builtin_amdgcn_mfma_f32_16x16x32_f16(Bt[n][k], At[m][k], acc[ai][bj][m][n], 0, 0, 0); __builtin_amdgcn_s_setprio(0); } while (0)
; #define PG8_WAIT_V(n) asm volatile("s_waitcnt vmcnt(" #n ")" ::: "memory")
; #define PG8_WAIT_L(n) asm volatile("s_waitcnt lgkmcnt(" #n ")" ::: "memory")
; #define PG8_BAR __builtin_amdgcn_s_barrier()
; #define PG8_SCHED __builtin_amdgcn_sched_barrier(0)
; template <class Epi>
; __device__ __forceinline__ void gemm_phase(LAS unsigned char* lds, const Gemm g, const StaticOrder& S, const Epi& E) {
;     ...
;             PG8_BAR; PG8_WAIT_L(0); PG8_MMA(1, 0, At, B0); PG8_BAR; PG8_SCHED;
;             PG8_STAGE(PG8_SB(0, 1), b2 + hstep, voffB);
;             PG8_WAIT_V(6); PG8_BAR; PG8_MMA(1, 1, At, B1); PG8_BAR;
;             PG8_LDB(B0, 1, 0); PG8_SCHED; PG8_LDA(At, 1, 0); PG8_STAGE(PG8_SA(0, 1), a2 + hstep, voffA);
;             PG8_WAIT_L(8); PG8_BAR; PG8_WAIT_L(0); PG8_MMA(0, 0, At, B0); PG8_BAR; PG8_SCHED;
;             PG8_LDB(B1, 1, 1); PG8_STAGE(PG8_SB(1, 0), b3, voffB);
;             PG8_BAR; PG8_WAIT_L(0); PG8_MMA(0, 1, At, B1); PG8_BAR;
;             PG8_LDA(At, 1, 1); PG8_STAGE(PG8_SA(1, 0), a3, voffA);
;             PG8_BAR; PG8_WAIT_L(0); PG8_MMA(1, 0, At, B0); PG8_BAR; PG8_SCHED;
;             PG8_STAGE(PG8_SB(1, 1), b3 + hstep, voffB);
;             PG8_WAIT_V(6); PG8_BAR; PG8_MMA(1, 1, At, B1); PG8_BAR;
	s_add_u32 s56, s34, 0x100000
	s_addc_u32 s57, s35, 0
	s_add_i32 s55, s50, s42
	v_lshl_add_u64 v[156:157], s[56:57], 0, v[140:141]
	s_mov_b32 m0, s55
	s_nop 0
	global_load_lds_dwordx4 v[156:157], off
	v_lshl_add_u64 v[156:157], s[56:57], 0, v[144:145]
	s_add_i32 m0, s55, 0x2000
	s_nop 0
	global_load_lds_dwordx4 v[156:157], off
	s_waitcnt vmcnt(6)
	s_barrier
	s_setprio 1
	v_mfma_f32_16x16x32_f16 v[52:55], v[208:211], v[176:179], v[52:55]
	v_mfma_f32_16x16x32_f16 v[48:51], v[216:219], v[176:179], v[48:51]
	v_mfma_f32_16x16x32_f16 v[36:39], v[208:211], v[184:187], v[36:39]
	v_mfma_f32_16x16x32_f16 v[32:35], v[216:219], v[184:187], v[32:35]
	v_mfma_f32_16x16x32_f16 v[20:23], v[208:211], v[192:195], v[20:23]
	v_mfma_f32_16x16x32_f16 v[16:19], v[216:219], v[192:195], v[16:19]
	v_mfma_f32_16x16x32_f16 v[4:7], v[208:211], v[200:203], v[4:7]
	v_mfma_f32_16x16x32_f16 v[0:3], v[216:219], v[200:203], v[0:3]
	v_mfma_f32_16x16x32_f16 v[52:55], v[212:215], v[180:183], v[52:55]
	v_mfma_f32_16x16x32_f16 v[48:51], v[220:223], v[180:183], v[48:51]
	v_mfma_f32_16x16x32_f16 v[36:39], v[212:215], v[188:191], v[36:39]
	v_mfma_f32_16x16x32_f16 v[32:35], v[220:223], v[188:191], v[32:35]
	v_mfma_f32_16x16x32_f16 v[20:23], v[212:215], v[196:199], v[20:23]
	v_mfma_f32_16x16x32_f16 v[16:19], v[220:223], v[196:199], v[16:19]
	v_mfma_f32_16x16x32_f16 v[4:7], v[212:215], v[204:207], v[4:7]
	v_mfma_f32_16x16x32_f16 v[0:3], v[220:223], v[204:207], v[0:3]
	s_setprio 0
	s_add_i32 s55, 0, 0x18000
	v_add_u32_e32 v172, s55, v147
	s_barrier
	ds_read_b128 v[156:159], v172
	ds_read_b128 v[164:167], v172 offset:1024
	ds_read_b128 v[168:171], v172 offset:2048
	ds_read_b128 v[172:175], v172 offset:3072
	s_add_u32 s36, s36, 0x100000
	s_addc_u32 s37, s37, 0
	s_mov_b32 m0, s44
	v_lshl_add_u64 v[208:209], s[36:37], 0, v[138:139]
	ds_read_b128 v[176:179], v162 offset:32768
	ds_read_b128 v[180:183], v162 offset:33792
	ds_read_b128 v[184:187], v162 offset:34816
	ds_read_b128 v[188:191], v162 offset:35840
	ds_read_b128 v[192:195], v162 offset:36864
	ds_read_b128 v[196:199], v162 offset:37888
	ds_read_b128 v[200:203], v162 offset:38912
	ds_read_b128 v[204:207], v162 offset:39936
	global_load_lds_dwordx4 v[208:209], off
	v_lshl_add_u64 v[208:209], s[36:37], 0, v[142:143]
	s_mov_b32 m0, s45
	s_nop 0
	global_load_lds_dwordx4 v[208:209], off
	s_waitcnt lgkmcnt(8)
	s_barrier
	s_waitcnt lgkmcnt(0)
	s_setprio 1
	s_waitcnt lgkmcnt(0)
	v_mfma_f32_16x16x32_f16 v[124:127], v[156:159], v[176:179], v[124:127]
	v_mfma_f32_16x16x32_f16 v[120:123], v[168:171], v[176:179], v[120:123]
	v_mfma_f32_16x16x32_f16 v[108:111], v[156:159], v[184:187], v[108:111]
	v_mfma_f32_16x16x32_f16 v[104:107], v[168:171], v[184:187], v[104:107]
	v_mfma_f32_16x16x32_f16 v[92:95], v[156:159], v[192:195], v[92:95]
	v_mfma_f32_16x16x32_f16 v[88:91], v[168:171], v[192:195], v[88:91]
	v_mfma_f32_16x16x32_f16 v[76:79], v[156:159], v[200:203], v[76:79]
	v_mfma_f32_16x16x32_f16 v[72:75], v[168:171], v[200:203], v[72:75]
	v_mfma_f32_16x16x32_f16 v[124:127], v[164:167], v[180:183], v[124:127]
	v_mfma_f32_16x16x32_f16 v[120:123], v[172:175], v[180:183], v[120:123]
	v_mfma_f32_16x16x32_f16 v[108:111], v[164:167], v[188:191], v[108:111]
	v_mfma_f32_16x16x32_f16 v[104:107], v[172:175], v[188:191], v[104:107]
	v_mfma_f32_16x16x32_f16 v[92:95], v[164:167], v[196:199], v[92:95]
	v_mfma_f32_16x16x32_f16 v[88:91], v[172:175], v[196:199], v[88:91]
	v_mfma_f32_16x16x32_f16 v[76:79], v[164:167], v[204:207], v[76:79]
	v_mfma_f32_16x16x32_f16 v[72:75], v[172:175], v[204:207], v[72:75]
	s_setprio 0
	s_barrier
	s_add_i32 s36, 0, 0x1c000
	s_add_i32 s37, s55, s42
	v_add_u32_e32 v220, s36, v147
	v_lshl_add_u64 v[224:225], v[224:225], 0, s[0:1]
	s_mov_b32 m0, s37
	ds_read_b128 v[208:211], v220
	ds_read_b128 v[212:215], v220 offset:1024
	ds_read_b128 v[216:219], v220 offset:2048
	ds_read_b128 v[220:223], v220 offset:3072
	global_load_lds_dwordx4 v[224:225], off
	v_lshl_add_u64 v[224:225], v[226:227], 0, s[0:1]
	s_add_i32 m0, s37, 0x2000
	s_nop 0
	global_load_lds_dwordx4 v[224:225], off
	s_barrier
	s_waitcnt lgkmcnt(0)
	s_setprio 1
	s_waitcnt lgkmcnt(0)
	v_mfma_f32_16x16x32_f16 v[116:119], v[208:211], v[176:179], v[116:119]
	v_mfma_f32_16x16x32_f16 v[112:115], v[216:219], v[176:179], v[112:115]
	v_mfma_f32_16x16x32_f16 v[100:103], v[208:211], v[184:187], v[100:103]
	v_mfma_f32_16x16x32_f16 v[96:99], v[216:219], v[184:187], v[96:99]
	v_mfma_f32_16x16x32_f16 v[84:87], v[208:211], v[192:195], v[84:87]
	v_mfma_f32_16x16x32_f16 v[80:83], v[216:219], v[192:195], v[80:83]
	v_mfma_f32_16x16x32_f16 v[68:71], v[208:211], v[200:203], v[68:71]
	v_mfma_f32_16x16x32_f16 v[64:67], v[216:219], v[200:203], v[64:67]
	v_mfma_f32_16x16x32_f16 v[116:119], v[212:215], v[180:183], v[116:119]
	v_mfma_f32_16x16x32_f16 v[112:115], v[220:223], v[180:183], v[112:115]
	v_mfma_f32_16x16x32_f16 v[100:103], v[212:215], v[188:191], v[100:103]
	v_mfma_f32_16x16x32_f16 v[96:99], v[220:223], v[188:191], v[96:99]
	v_mfma_f32_16x16x32_f16 v[84:87], v[212:215], v[196:199], v[84:87]
	v_mfma_f32_16x16x32_f16 v[80:83], v[220:223], v[196:199], v[80:83]
	v_mfma_f32_16x16x32_f16 v[68:71], v[212:215], v[204:207], v[68:71]
	v_mfma_f32_16x16x32_f16 v[64:67], v[220:223], v[204:207], v[64:67]
	s_setprio 0
	s_mov_b32 m0, s47
	v_lshl_add_u64 v[224:225], v[228:229], 0, s[0:1]
	s_barrier
	ds_read_b128 v[176:179], v162 offset:49152
	ds_read_b128 v[180:183], v162 offset:50176
	ds_read_b128 v[184:187], v162 offset:51200
	ds_read_b128 v[188:191], v162 offset:52224
	ds_read_b128 v[192:195], v162 offset:53248
	ds_read_b128 v[196:199], v162 offset:54272
	ds_read_b128 v[200:203], v162 offset:55296
	ds_read_b128 v[204:207], v162 offset:56320
	global_load_lds_dwordx4 v[224:225], off
	v_lshl_add_u64 v[224:225], v[230:231], 0, s[0:1]
	s_mov_b32 m0, s48
	s_nop 0
	global_load_lds_dwordx4 v[224:225], off
	s_barrier
; #define PG8_BAR __builtin_amdgcn_s_barrier()
; template <class Epi>
; __device__ __forceinline__ void gemm_phase(LAS unsigned char* lds, const Gemm g, const StaticOrder& S, const Epi& E) {
;     ...
;             PG8_BAR; PG8_WAIT_L(0); PG8_MMA(1, 0, At, B0); PG8_BAR; PG8_SCHED;
;             PG8_STAGE(PG8_SB(1, 1), b3 + hstep, voffB);
;             PG8_WAIT_V(6); PG8_BAR; PG8_MMA(1, 1, At, B1); PG8_BAR;
;     __device__ __forceinline__ void operator()(const f32x4 (&acc)[2][2][4][2], const pg8::Unit& u, int wr, int wc, int fr, int fq) const {
;         const int row0 = u.pm * 256 + wr * 64 + fr, col0 = u.pn * 256 + wc * 32 + 8 * fq;
; #pragma unroll
;         for (int ai = 0; ai < 2; ++ai)
; #pragma unroll
;             for (int m = 0; m < 4; ++m) {
;                 const int row = row0 + ai * 128 + m * 16;
;                 float ss = 0.f, rstd = 1.f;
;                 if (MODE == 2) rstd = rsqrtf(rowss[row] * (1.f / 1024.f) + EPS);
; #pragma unroll
;                 for (int bj = 0; bj < 2; ++bj) {
;                     const int c = col0 + bj * 128;
;                     f32x4 v0 = acc[ai][bj][m][0], v1 = acc[ai][bj][m][1];
;                     if (MODE == 1) {
;                         const float* rp = res + (size_t)row * ldres + c;
;                         v0 += *(const f32x4*)rp; v1 += *(const f32x4*)(rp + 4);
;                     }
;                     if (MODE == 3) {
;                         const h16x8 r8 = *(const h16x8*)(res16 + (size_t)row * ldres + c);
; #pragma unroll
;                         for (int j = 0; j < 4; ++j) { v0[j] += (float)r8[j]; v1[j] += (float)r8[4 + j]; }
;                     }
;                     if (MODE == 1 || MODE == 3) {
;                         ss += v0[0] * v0[0] + v0[1] * v0[1] + v0[2] * v0[2] + v0[3] * v0[3] + v1[0] * v1[0] + v1[1] * v1[1] + v1[2] * v1[2] + v1[3] * v1[3];
;                     }
;                     if (MODE == 2) {
; #pragma unroll
;                         for (int j = 0; j < 4; ++j) { float a = fmaxf(v0[j] * rstd, 0.f), b = fmaxf(v1[j] * rstd, 0.f); v0[j] = a * a; v1[j] = b * b; }
;                     }
;                     *(h16x8*)(o16 + (size_t)row * ld16 + c) = pack8(v0, v1);
;                 }
;                 if (MODE == 1 || MODE == 3) {
;                     ss += __shfl_xor(ss, 16); ss += __shfl_xor(ss, 32);
;                     if (fq == 0) atomicAdd(rowss + row, ss);
	s_waitcnt lgkmcnt(0)
	s_setprio 1
	s_waitcnt lgkmcnt(0)
	v_mfma_f32_16x16x32_f16 v[60:63], v[156:159], v[176:179], v[60:63]
	v_mfma_f32_16x16x32_f16 v[56:59], v[168:171], v[176:179], v[56:59]
	v_mfma_f32_16x16x32_f16 v[44:47], v[156:159], v[184:187], v[44:47]
	v_mfma_f32_16x16x32_f16 v[40:43], v[168:171], v[184:187], v[40:43]
	v_mfma_f32_16x16x32_f16 v[28:31], v[156:159], v[192:195], v[28:31]
	v_mfma_f32_16x16x32_f16 v[24:27], v[168:171], v[192:195], v[24:27]
	v_mfma_f32_16x16x32_f16 v[12:15], v[156:159], v[200:203], v[12:15]
	v_mfma_f32_16x16x32_f16 v[8:11], v[168:171], v[200:203], v[8:11]
	v_mfma_f32_16x16x32_f16 v[60:63], v[164:167], v[180:183], v[60:63]
	v_mfma_f32_16x16x32_f16 v[56:59], v[172:175], v[180:183], v[56:59]
	v_mfma_f32_16x16x32_f16 v[44:47], v[164:167], v[188:191], v[44:47]
	v_mfma_f32_16x16x32_f16 v[40:43], v[172:175], v[188:191], v[40:43]
	v_mfma_f32_16x16x32_f16 v[28:31], v[164:167], v[196:199], v[28:31]
	v_mfma_f32_16x16x32_f16 v[24:27], v[172:175], v[196:199], v[24:27]
	v_mfma_f32_16x16x32_f16 v[12:15], v[164:167], v[204:207], v[12:15]
	v_mfma_f32_16x16x32_f16 v[8:11], v[172:175], v[204:207], v[8:11]
	s_setprio 0
	s_barrier
	s_add_u32 s34, s34, 0x100080
	s_addc_u32 s35, s35, 0
	s_add_i32 s36, s36, s42
	v_lshl_add_u64 v[156:157], s[34:35], 0, v[140:141]
	s_mov_b32 m0, s36
	s_nop 0
	global_load_lds_dwordx4 v[156:157], off
	v_lshl_add_u64 v[156:157], s[34:35], 0, v[144:145]
	s_add_i32 m0, s36, 0x2000
	s_nop 0
	global_load_lds_dwordx4 v[156:157], off
	s_waitcnt vmcnt(6)
	s_barrier
	s_setprio 1
	v_mfma_f32_16x16x32_f16 v[52:55], v[208:211], v[176:179], v[52:55]
	v_mfma_f32_16x16x32_f16 v[48:51], v[216:219], v[176:179], v[48:51]
	v_mfma_f32_16x16x32_f16 v[36:39], v[208:211], v[184:187], v[36:39]
	v_mfma_f32_16x16x32_f16 v[32:35], v[216:219], v[184:187], v[32:35]
	v_mfma_f32_16x16x32_f16 v[20:23], v[208:211], v[192:195], v[20:23]
	v_mfma_f32_16x16x32_f16 v[16:19], v[216:219], v[192:195], v[16:19]
	v_mfma_f32_16x16x32_f16 v[4:7], v[208:211], v[200:203], v[4:7]
	v_mfma_f32_16x16x32_f16 v[0:3], v[216:219], v[200:203], v[0:3]
	v_mfma_f32_16x16x32_f16 v[52:55], v[212:215], v[180:183], v[52:55]
	v_mfma_f32_16x16x32_f16 v[48:51], v[220:223], v[180:183], v[48:51]
	v_mfma_f32_16x16x32_f16 v[36:39], v[212:215], v[188:191], v[36:39]
	v_mfma_f32_16x16x32_f16 v[32:35], v[220:223], v[188:191], v[32:35]
	v_mfma_f32_16x16x32_f16 v[20:23], v[212:215], v[196:199], v[20:23]
	v_mfma_f32_16x16x32_f16 v[16:19], v[220:223], v[196:199], v[16:19]
	v_mfma_f32_16x16x32_f16 v[4:7], v[212:215], v[204:207], v[4:7]
	v_mfma_f32_16x16x32_f16 v[0:3], v[220:223], v[204:207], v[0:3]
	s_setprio 0
	s_add_i32 s54, s54, 2
	s_add_u32 s30, s30, 0x100
	s_addc_u32 s31, s31, 0
	s_add_u32 s52, s52, 0x100
	s_addc_u32 s53, s53, 0
	s_cmp_gt_u32 s54, 61
	s_barrier
	s_cbranch_scc0 .LBB0_531
	v_lshl_add_u32 v158, s26, 8, v137
	v_lshl_or_b32 v156, s28, 8, v160
	v_ashrrev_i32_e32 v159, 31, v158
	v_lshlrev_b64 v[174:175], 11, v[158:159]
	v_ashrrev_i32_e32 v157, 31, v156
	v_lshl_add_u64 v[164:165], s[10:11], 0, v[174:175]
	v_lshlrev_b64 v[156:157], 1, v[156:157]
	v_lshl_add_u64 v[164:165], v[164:165], 0, v[156:157]
	global_load_dwordx4 v[166:169], v[164:165], off
	global_load_dwordx4 v[170:173], v[164:165], off offset:256
	v_xor_b32_e32 v164, 16, v129
	v_xor_b32_e32 v165, 32, v129
	v_cmp_lt_i32_e32 vcc, v164, v135
	s_waitcnt vmcnt(0)
	v_cvt_f32_f16_sdwa v177, v166 dst_sel:DWORD dst_unused:UNUSED_PAD src0_sel:WORD_1
	v_cndmask_b32_e32 v164, v129, v164, vcc
	v_cmp_lt_i32_e32 vcc, v165, v135
	v_cvt_f32_f16_e32 v178, v168
	v_cvt_f32_f16_sdwa v179, v168 dst_sel:DWORD dst_unused:UNUSED_PAD src0_sel:WORD_1
	v_cndmask_b32_e32 v176, v129, v165, vcc
	v_lshlrev_b32_e32 v165, 2, v164
	v_lshlrev_b32_e32 v164, 2, v176
	v_cvt_f32_f16_e32 v176, v166
	v_cvt_f32_f16_e32 v166, v167
	v_cvt_f32_f16_sdwa v167, v167 dst_sel:DWORD dst_unused:UNUSED_PAD src0_sel:WORD_1
	v_cvt_f32_f16_e32 v168, v169
	v_cvt_f32_f16_sdwa v169, v169 dst_sel:DWORD dst_unused:UNUSED_PAD src0_sel:WORD_1
	v_cvt_f32_f16_e32 v180, v170
	v_cvt_f32_f16_sdwa v181, v170 dst_sel:DWORD dst_unused:UNUSED_PAD src0_sel:WORD_1
	v_cvt_f32_f16_e32 v170, v171
	v_cvt_f32_f16_sdwa v171, v171 dst_sel:DWORD dst_unused:UNUSED_PAD src0_sel:WORD_1
	v_cvt_f32_f16_e32 v182, v172
	v_cvt_f32_f16_sdwa v183, v172 dst_sel:DWORD dst_unused:UNUSED_PAD src0_sel:WORD_1
	v_cvt_f32_f16_e32 v172, v173
	v_cvt_f32_f16_sdwa v173, v173 dst_sel:DWORD dst_unused:UNUSED_PAD src0_sel:WORD_1
	v_pk_add_f32 v[124:125], v[124:125], v[176:177]
	v_pk_add_f32 v[126:127], v[126:127], v[166:167]
	v_pk_add_f32 v[120:121], v[120:121], v[178:179]
	v_pk_add_f32 v[122:123], v[122:123], v[168:169]
	v_pk_add_f32 v[116:117], v[116:117], v[180:181]
	v_pk_add_f32 v[118:119], v[118:119], v[170:171]
	v_pk_add_f32 v[166:167], v[112:113], v[182:183]
	v_pk_add_f32 v[168:169], v[114:115], v[172:173]
	v_pk_mul_f32 v[170:171], v[124:125], v[124:125]
	v_cvt_pk_f16_f32 v112, v124, v125
	v_pk_mul_f32 v[124:125], v[126:127], v[126:127]
	v_cvt_pk_f16_f32 v113, v126, v127
	v_pk_mul_f32 v[126:127], v[120:121], v[120:121]
	v_cvt_pk_f16_f32 v114, v120, v121
	v_pk_mul_f32 v[120:121], v[122:123], v[122:123]
	v_cvt_pk_f16_f32 v115, v122, v123
	v_pk_mul_f32 v[122:123], v[116:117], v[116:117]
	v_pk_mul_f32 v[172:173], v[118:119], v[118:119]
	v_add_f32_e32 v122, v122, v123
	v_add_f32_e32 v123, v170, v171
	v_add_f32_e32 v122, v172, v122
	v_add_f32_e32 v123, v124, v123
	v_pk_mul_f32 v[176:177], v[166:167], v[166:167]
	v_add_f32_e32 v122, v173, v122
	v_add_f32_e32 v123, v125, v123
	v_add_f32_e32 v122, v176, v122
	v_add_f32_e32 v123, v126, v123
	v_pk_mul_f32 v[178:179], v[168:169], v[168:169]
	v_add_f32_e32 v122, v177, v122
	v_add_f32_e32 v123, v127, v123
	v_add_f32_e32 v122, v178, v122
	v_add_f32_e32 v120, v120, v123
	v_add_f32_e32 v122, v179, v122
	v_add_f32_e32 v120, v121, v120
	v_add_f32_e32 v122, v120, v122
	ds_bpermute_b32 v123, v165, v122
	v_lshl_add_u64 v[120:121], s[86:87], 0, v[174:175]
	v_lshl_add_u64 v[120:121], v[120:121], 0, v[156:157]
	global_store_dwordx4 v[120:121], v[112:115], off sc0 sc1
	s_waitcnt lgkmcnt(0)
	s_nop 0
	v_add_f32_e32 v112, v122, v123
	ds_bpermute_b32 v113, v164, v112
	v_cvt_pk_f16_f32 v114, v116, v117
	v_cvt_pk_f16_f32 v115, v118, v119
	v_cvt_pk_f16_f32 v116, v166, v167
	v_cvt_pk_f16_f32 v117, v168, v169
	global_store_dwordx4 v[120:121], v[114:117], off offset:256 sc0 sc1
	s_and_saveexec_b64 s[26:27], s[6:7]
	s_cbranch_execz .LBB0_534
	v_lshl_add_u64 v[114:115], v[158:159], 2, s[14:15]
	s_waitcnt lgkmcnt(0)
	v_add_f32_e32 v112, v112, v113
	global_atomic_add_f32 v[114:115], v112, off
;     __device__ __forceinline__ void operator()(const f32x4 (&acc)[2][2][4][2], const pg8::Unit& u, int wr, int wc, int fr, int fq) const {
;     ...
;         for (int ai = 0; ai < 2; ++ai)
; #pragma unroll
;             for (int m = 0; m < 4; ++m) {
;                 const int row = row0 + ai * 128 + m * 16;
;                 float ss = 0.f, rstd = 1.f;
;                 if (MODE == 2) rstd = rsqrtf(rowss[row] * (1.f / 1024.f) + EPS);
; #pragma unroll
;                 for (int bj = 0; bj < 2; ++bj) {
;                     const int c = col0 + bj * 128;
;                     f32x4 v0 = acc[ai][bj][m][0], v1 = acc[ai][bj][m][1];
;                     if (MODE == 1) {
;                         const float* rp = res + (size_t)row * ldres + c;
;                         v0 += *(const f32x4*)rp; v1 += *(const f32x4*)(rp + 4);
;                     }
;                     if (MODE == 3) {
;                         const h16x8 r8 = *(const h16x8*)(res16 + (size_t)row * ldres + c);
; #pragma unroll
;                         for (int j = 0; j < 4; ++j) { v0[j] += (float)r8[j]; v1[j] += (float)r8[4 + j]; }
;                     }
;                     if (MODE == 1 || MODE == 3) {
;                         ss += v0[0] * v0[0] + v0[1] * v0[1] + v0[2] * v0[2] + v0[3] * v0[3] + v1[0] * v1[0] + v1[1] * v1[1] + v1[2] * v1[2] + v1[3] * v1[3];
;                     }
;                     if (MODE == 2) {
; #pragma unroll
;                         for (int j = 0; j < 4; ++j) { float a = fmaxf(v0[j] * rstd, 0.f), b = fmaxf(v1[j] * rstd, 0.f); v0[j] = a * a; v1[j] = b * b; }
;                     }
;                     *(h16x8*)(o16 + (size_t)row * ld16 + c) = pack8(v0, v1);
;                 }
;                 if (MODE == 1 || MODE == 3) {
;                     ss += __shfl_xor(ss, 16); ss += __shfl_xor(ss, 32);
;                     if (fq == 0) atomicAdd(rowss + row, ss);
;                 }
.LBB0_534:
	s_or_b64 exec, exec, s[26:27]
	v_or_b32_e32 v112, 16, v158
	s_waitcnt lgkmcnt(0)
	v_ashrrev_i32_e32 v113, 31, v112
	v_lshlrev_b64 v[122:123], 11, v[112:113]
	v_lshl_add_u64 v[114:115], s[10:11], 0, v[122:123]
	v_lshl_add_u64 v[118:119], v[114:115], 0, v[156:157]
	global_load_dwordx4 v[114:117], v[118:119], off
	s_nop 0
	global_load_dwordx4 v[118:121], v[118:119], off offset:256
	s_waitcnt vmcnt(1)
	v_cvt_f32_f16_e32 v124, v114
	v_cvt_f32_f16_sdwa v125, v114 dst_sel:DWORD dst_unused:UNUSED_PAD src0_sel:WORD_1
	v_cvt_f32_f16_e32 v114, v115
	v_cvt_f32_f16_sdwa v115, v115 dst_sel:DWORD dst_unused:UNUSED_PAD src0_sel:WORD_1
	v_cvt_f32_f16_e32 v126, v116
	v_cvt_f32_f16_sdwa v127, v116 dst_sel:DWORD dst_unused:UNUSED_PAD src0_sel:WORD_1
	v_cvt_f32_f16_e32 v116, v117
	v_cvt_f32_f16_sdwa v117, v117 dst_sel:DWORD dst_unused:UNUSED_PAD src0_sel:WORD_1
	s_waitcnt vmcnt(0)
	v_cvt_f32_f16_e32 v166, v118
	v_cvt_f32_f16_sdwa v167, v118 dst_sel:DWORD dst_unused:UNUSED_PAD src0_sel:WORD_1
	v_cvt_f32_f16_e32 v118, v119
	v_cvt_f32_f16_sdwa v119, v119 dst_sel:DWORD dst_unused:UNUSED_PAD src0_sel:WORD_1
	v_cvt_f32_f16_e32 v168, v120
	v_cvt_f32_f16_sdwa v169, v120 dst_sel:DWORD dst_unused:UNUSED_PAD src0_sel:WORD_1
	v_cvt_f32_f16_e32 v120, v121
	v_cvt_f32_f16_sdwa v121, v121 dst_sel:DWORD dst_unused:UNUSED_PAD src0_sel:WORD_1
	v_pk_add_f32 v[108:109], v[108:109], v[124:125]
	v_pk_add_f32 v[110:111], v[110:111], v[114:115]
	v_pk_add_f32 v[104:105], v[104:105], v[126:127]
	v_pk_add_f32 v[106:107], v[106:107], v[116:117]
	v_pk_add_f32 v[100:101], v[100:101], v[166:167]
	v_pk_add_f32 v[102:103], v[102:103], v[118:119]
	v_pk_add_f32 v[114:115], v[96:97], v[168:169]
	v_pk_add_f32 v[116:117], v[98:99], v[120:121]
	v_pk_mul_f32 v[118:119], v[108:109], v[108:109]
	v_cvt_pk_f16_f32 v96, v108, v109
	v_pk_mul_f32 v[108:109], v[110:111], v[110:111]
	v_cvt_pk_f16_f32 v97, v110, v111
	v_pk_mul_f32 v[110:111], v[104:105], v[104:105]
	v_cvt_pk_f16_f32 v98, v104, v105
	v_pk_mul_f32 v[104:105], v[106:107], v[106:107]
	v_cvt_pk_f16_f32 v99, v106, v107
	v_pk_mul_f32 v[106:107], v[100:101], v[100:101]
	v_pk_mul_f32 v[120:121], v[102:103], v[102:103]
	v_add_f32_e32 v106, v106, v107
	v_add_f32_e32 v107, v118, v119
	v_add_f32_e32 v106, v120, v106
	v_add_f32_e32 v107, v108, v107
	v_pk_mul_f32 v[124:125], v[114:115], v[114:115]
	v_add_f32_e32 v106, v121, v106
	v_add_f32_e32 v107, v109, v107
	v_add_f32_e32 v106, v124, v106
	v_add_f32_e32 v107, v110, v107
	v_pk_mul_f32 v[126:127], v[116:117], v[116:117]
	v_add_f32_e32 v106, v125, v106
	v_add_f32_e32 v107, v111, v107
	v_add_f32_e32 v106, v126, v106
	v_add_f32_e32 v104, v104, v107
	v_add_f32_e32 v106, v127, v106
	v_add_f32_e32 v104, v105, v104
	v_add_f32_e32 v106, v104, v106
	ds_bpermute_b32 v107, v165, v106
	v_lshl_add_u64 v[104:105], s[86:87], 0, v[122:123]
	v_lshl_add_u64 v[104:105], v[104:105], 0, v[156:157]
	global_store_dwordx4 v[104:105], v[96:99], off sc0 sc1
	s_waitcnt lgkmcnt(0)
	s_nop 0
	v_add_f32_e32 v96, v106, v107
	ds_bpermute_b32 v97, v164, v96
	v_cvt_pk_f16_f32 v98, v100, v101
	v_cvt_pk_f16_f32 v99, v102, v103
	v_cvt_pk_f16_f32 v100, v114, v115
	v_cvt_pk_f16_f32 v101, v116, v117
	global_store_dwordx4 v[104:105], v[98:101], off offset:256 sc0 sc1
	s_and_saveexec_b64 s[26:27], s[6:7]
	s_cbranch_execz .LBB0_536
	v_lshl_add_u64 v[98:99], v[112:113], 2, s[14:15]
	s_waitcnt lgkmcnt(0)
	v_add_f32_e32 v96, v96, v97
	global_atomic_add_f32 v[98:99], v96, off
.LBB0_536:
	s_or_b64 exec, exec, s[26:27]
	v_or_b32_e32 v96, 32, v158
	s_waitcnt lgkmcnt(0)
	v_ashrrev_i32_e32 v97, 31, v96
	v_lshlrev_b64 v[106:107], 11, v[96:97]
	v_lshl_add_u64 v[98:99], s[10:11], 0, v[106:107]
	v_lshl_add_u64 v[102:103], v[98:99], 0, v[156:157]
	global_load_dwordx4 v[98:101], v[102:103], off
	s_nop 0
	global_load_dwordx4 v[102:105], v[102:103], off offset:256
	s_waitcnt vmcnt(1)
	v_cvt_f32_f16_e32 v108, v98
	v_cvt_f32_f16_sdwa v109, v98 dst_sel:DWORD dst_unused:UNUSED_PAD src0_sel:WORD_1
	v_cvt_f32_f16_e32 v98, v99
	v_cvt_f32_f16_sdwa v99, v99 dst_sel:DWORD dst_unused:UNUSED_PAD src0_sel:WORD_1
	v_cvt_f32_f16_e32 v110, v100
	v_cvt_f32_f16_sdwa v111, v100 dst_sel:DWORD dst_unused:UNUSED_PAD src0_sel:WORD_1
	v_cvt_f32_f16_e32 v100, v101
	v_cvt_f32_f16_sdwa v101, v101 dst_sel:DWORD dst_unused:UNUSED_PAD src0_sel:WORD_1
	s_waitcnt vmcnt(0)
	v_cvt_f32_f16_e32 v112, v102
	v_cvt_f32_f16_sdwa v113, v102 dst_sel:DWORD dst_unused:UNUSED_PAD src0_sel:WORD_1
	v_cvt_f32_f16_e32 v102, v103
	v_cvt_f32_f16_sdwa v103, v103 dst_sel:DWORD dst_unused:UNUSED_PAD src0_sel:WORD_1
	v_cvt_f32_f16_e32 v114, v104
	v_cvt_f32_f16_sdwa v115, v104 dst_sel:DWORD dst_unused:UNUSED_PAD src0_sel:WORD_1
	v_cvt_f32_f16_e32 v104, v105
	v_cvt_f32_f16_sdwa v105, v105 dst_sel:DWORD dst_unused:UNUSED_PAD src0_sel:WORD_1
	v_pk_add_f32 v[92:93], v[92:93], v[108:109]
	v_pk_add_f32 v[94:95], v[94:95], v[98:99]
	v_pk_add_f32 v[88:89], v[88:89], v[110:111]
	v_pk_add_f32 v[90:91], v[90:91], v[100:101]
	v_pk_add_f32 v[84:85], v[84:85], v[112:113]
	v_pk_add_f32 v[86:87], v[86:87], v[102:103]
	v_pk_add_f32 v[98:99], v[80:81], v[114:115]
	v_pk_add_f32 v[100:101], v[82:83], v[104:105]
	v_pk_mul_f32 v[102:103], v[92:93], v[92:93]
	v_cvt_pk_f16_f32 v80, v92, v93
	v_pk_mul_f32 v[92:93], v[94:95], v[94:95]
	v_cvt_pk_f16_f32 v81, v94, v95
	v_pk_mul_f32 v[94:95], v[88:89], v[88:89]
	v_cvt_pk_f16_f32 v82, v88, v89
	v_pk_mul_f32 v[88:89], v[90:91], v[90:91]
	v_cvt_pk_f16_f32 v83, v90, v91
	v_pk_mul_f32 v[90:91], v[84:85], v[84:85]
	v_pk_mul_f32 v[104:105], v[86:87], v[86:87]
	v_add_f32_e32 v90, v90, v91
	v_add_f32_e32 v91, v102, v103
	v_add_f32_e32 v90, v104, v90
	v_add_f32_e32 v91, v92, v91
	v_pk_mul_f32 v[108:109], v[98:99], v[98:99]
	v_add_f32_e32 v90, v105, v90
	v_add_f32_e32 v91, v93, v91
	v_add_f32_e32 v90, v108, v90
	v_add_f32_e32 v91, v94, v91
	v_pk_mul_f32 v[110:111], v[100:101], v[100:101]
	v_add_f32_e32 v90, v109, v90
	v_add_f32_e32 v91, v95, v91
	v_add_f32_e32 v90, v110, v90
	v_add_f32_e32 v88, v88, v91
	v_add_f32_e32 v90, v111, v90
	v_add_f32_e32 v88, v89, v88
	v_add_f32_e32 v90, v88, v90
	ds_bpermute_b32 v91, v165, v90
	v_lshl_add_u64 v[88:89], s[86:87], 0, v[106:107]
	v_lshl_add_u64 v[88:89], v[88:89], 0, v[156:157]
	global_store_dwordx4 v[88:89], v[80:83], off sc0 sc1
	s_waitcnt lgkmcnt(0)
	s_nop 0
	v_add_f32_e32 v80, v90, v91
	ds_bpermute_b32 v81, v164, v80
	v_cvt_pk_f16_f32 v82, v84, v85
	v_cvt_pk_f16_f32 v83, v86, v87
	v_cvt_pk_f16_f32 v84, v98, v99
	v_cvt_pk_f16_f32 v85, v100, v101
	global_store_dwordx4 v[88:89], v[82:85], off offset:256 sc0 sc1
	s_and_saveexec_b64 s[26:27], s[6:7]
	s_cbranch_execz .LBB0_538
	v_lshl_add_u64 v[82:83], v[96:97], 2, s[14:15]
	s_waitcnt lgkmcnt(0)
	v_add_f32_e32 v80, v80, v81
	global_atomic_add_f32 v[82:83], v80, off
;     __device__ __forceinline__ void operator()(const f32x4 (&acc)[2][2][4][2], const pg8::Unit& u, int wr, int wc, int fr, int fq) const {
;     ...
;         for (int ai = 0; ai < 2; ++ai)
; #pragma unroll
;             for (int m = 0; m < 4; ++m) {
;                 const int row = row0 + ai * 128 + m * 16;
;                 float ss = 0.f, rstd = 1.f;
;                 if (MODE == 2) rstd = rsqrtf(rowss[row] * (1.f / 1024.f) + EPS);
; #pragma unroll
;                 for (int bj = 0; bj < 2; ++bj) {
;                     const int c = col0 + bj * 128;
;                     f32x4 v0 = acc[ai][bj][m][0], v1 = acc[ai][bj][m][1];
;                     if (MODE == 1) {
;                         const float* rp = res + (size_t)row * ldres + c;
;                         v0 += *(const f32x4*)rp; v1 += *(const f32x4*)(rp + 4);
;                     }
;                     if (MODE == 3) {
;                         const h16x8 r8 = *(const h16x8*)(res16 + (size_t)row * ldres + c);
; #pragma unroll
;                         for (int j = 0; j < 4; ++j) { v0[j] += (float)r8[j]; v1[j] += (float)r8[4 + j]; }
;                     }
;                     if (MODE == 1 || MODE == 3) {
;                         ss += v0[0] * v0[0] + v0[1] * v0[1] + v0[2] * v0[2] + v0[3] * v0[3] + v1[0] * v1[0] + v1[1] * v1[1] + v1[2] * v1[2] + v1[3] * v1[3];
;                     }
;                     if (MODE == 2) {
; #pragma unroll
;                         for (int j = 0; j < 4; ++j) { float a = fmaxf(v0[j] * rstd, 0.f), b = fmaxf(v1[j] * rstd, 0.f); v0[j] = a * a; v1[j] = b * b; }
;                     }
;                     *(h16x8*)(o16 + (size_t)row * ld16 + c) = pack8(v0, v1);
;                 }
;                 if (MODE == 1 || MODE == 3) {
;                     ss += __shfl_xor(ss, 16); ss += __shfl_xor(ss, 32);
;                     if (fq == 0) atomicAdd(rowss + row, ss);
;                 }
.LBB0_538:
	s_or_b64 exec, exec, s[26:27]
	v_or_b32_e32 v80, 48, v158
	s_waitcnt lgkmcnt(0)
	v_ashrrev_i32_e32 v81, 31, v80
	v_lshlrev_b64 v[90:91], 11, v[80:81]
	v_lshl_add_u64 v[82:83], s[10:11], 0, v[90:91]
	v_lshl_add_u64 v[86:87], v[82:83], 0, v[156:157]
	global_load_dwordx4 v[82:85], v[86:87], off
	s_nop 0
	global_load_dwordx4 v[86:89], v[86:87], off offset:256
	s_waitcnt vmcnt(1)
	v_cvt_f32_f16_e32 v92, v82
	v_cvt_f32_f16_sdwa v93, v82 dst_sel:DWORD dst_unused:UNUSED_PAD src0_sel:WORD_1
	v_cvt_f32_f16_e32 v82, v83
	v_cvt_f32_f16_sdwa v83, v83 dst_sel:DWORD dst_unused:UNUSED_PAD src0_sel:WORD_1
	v_cvt_f32_f16_e32 v94, v84
	v_cvt_f32_f16_sdwa v95, v84 dst_sel:DWORD dst_unused:UNUSED_PAD src0_sel:WORD_1
	v_cvt_f32_f16_e32 v84, v85
	v_cvt_f32_f16_sdwa v85, v85 dst_sel:DWORD dst_unused:UNUSED_PAD src0_sel:WORD_1
	s_waitcnt vmcnt(0)
	v_cvt_f32_f16_e32 v96, v86
	v_cvt_f32_f16_sdwa v97, v86 dst_sel:DWORD dst_unused:UNUSED_PAD src0_sel:WORD_1
	v_cvt_f32_f16_e32 v86, v87
	v_cvt_f32_f16_sdwa v87, v87 dst_sel:DWORD dst_unused:UNUSED_PAD src0_sel:WORD_1
	v_cvt_f32_f16_e32 v98, v88
	v_cvt_f32_f16_sdwa v99, v88 dst_sel:DWORD dst_unused:UNUSED_PAD src0_sel:WORD_1
	v_cvt_f32_f16_e32 v88, v89
	v_cvt_f32_f16_sdwa v89, v89 dst_sel:DWORD dst_unused:UNUSED_PAD src0_sel:WORD_1
	v_pk_add_f32 v[76:77], v[76:77], v[92:93]
	v_pk_add_f32 v[78:79], v[78:79], v[82:83]
	v_pk_add_f32 v[72:73], v[72:73], v[94:95]
	v_pk_add_f32 v[74:75], v[74:75], v[84:85]
	v_pk_add_f32 v[68:69], v[68:69], v[96:97]
	v_pk_add_f32 v[70:71], v[70:71], v[86:87]
	v_pk_add_f32 v[82:83], v[64:65], v[98:99]
	v_pk_add_f32 v[84:85], v[66:67], v[88:89]
	v_pk_mul_f32 v[86:87], v[76:77], v[76:77]
	v_cvt_pk_f16_f32 v64, v76, v77
	v_pk_mul_f32 v[76:77], v[78:79], v[78:79]
	v_cvt_pk_f16_f32 v65, v78, v79
	v_pk_mul_f32 v[78:79], v[72:73], v[72:73]
	v_cvt_pk_f16_f32 v66, v72, v73
	v_pk_mul_f32 v[72:73], v[74:75], v[74:75]
	v_cvt_pk_f16_f32 v67, v74, v75
	v_pk_mul_f32 v[74:75], v[68:69], v[68:69]
	v_pk_mul_f32 v[88:89], v[70:71], v[70:71]
	v_add_f32_e32 v74, v74, v75
	v_add_f32_e32 v75, v86, v87
	v_add_f32_e32 v74, v88, v74
	v_add_f32_e32 v75, v76, v75
	v_pk_mul_f32 v[92:93], v[82:83], v[82:83]
	v_add_f32_e32 v74, v89, v74
	v_add_f32_e32 v75, v77, v75
	v_add_f32_e32 v74, v92, v74
	v_add_f32_e32 v75, v78, v75
	v_pk_mul_f32 v[94:95], v[84:85], v[84:85]
	v_add_f32_e32 v74, v93, v74
	v_add_f32_e32 v75, v79, v75
	v_add_f32_e32 v74, v94, v74
	v_add_f32_e32 v72, v72, v75
	v_add_f32_e32 v74, v95, v74
	v_add_f32_e32 v72, v73, v72
	v_add_f32_e32 v74, v72, v74
	ds_bpermute_b32 v75, v165, v74
	v_lshl_add_u64 v[72:73], s[86:87], 0, v[90:91]
	v_lshl_add_u64 v[72:73], v[72:73], 0, v[156:157]
	global_store_dwordx4 v[72:73], v[64:67], off sc0 sc1
	s_waitcnt lgkmcnt(0)
	s_nop 0
	v_add_f32_e32 v64, v74, v75
	ds_bpermute_b32 v65, v164, v64
	v_cvt_pk_f16_f32 v66, v68, v69
	v_cvt_pk_f16_f32 v67, v70, v71
	v_cvt_pk_f16_f32 v68, v82, v83
	v_cvt_pk_f16_f32 v69, v84, v85
	global_store_dwordx4 v[72:73], v[66:69], off offset:256 sc0 sc1
	s_and_saveexec_b64 s[26:27], s[6:7]
	s_cbranch_execz .LBB0_540
	v_lshl_add_u64 v[66:67], v[80:81], 2, s[14:15]
	s_waitcnt lgkmcnt(0)
	v_add_f32_e32 v64, v64, v65
	global_atomic_add_f32 v[66:67], v64, off
.LBB0_540:
	s_or_b64 exec, exec, s[26:27]
	v_add_u32_e32 v64, 0x80, v158
	s_waitcnt lgkmcnt(0)
	v_ashrrev_i32_e32 v65, 31, v64
	v_lshlrev_b64 v[74:75], 11, v[64:65]
	v_lshl_add_u64 v[66:67], s[10:11], 0, v[74:75]
	v_lshl_add_u64 v[70:71], v[66:67], 0, v[156:157]
	global_load_dwordx4 v[66:69], v[70:71], off
	s_nop 0
	global_load_dwordx4 v[70:73], v[70:71], off offset:256
	s_waitcnt vmcnt(1)
	v_cvt_f32_f16_e32 v76, v66
	v_cvt_f32_f16_sdwa v77, v66 dst_sel:DWORD dst_unused:UNUSED_PAD src0_sel:WORD_1
	v_cvt_f32_f16_e32 v66, v67
	v_cvt_f32_f16_sdwa v67, v67 dst_sel:DWORD dst_unused:UNUSED_PAD src0_sel:WORD_1
	v_cvt_f32_f16_e32 v78, v68
	v_cvt_f32_f16_sdwa v79, v68 dst_sel:DWORD dst_unused:UNUSED_PAD src0_sel:WORD_1
	v_cvt_f32_f16_e32 v68, v69
	v_cvt_f32_f16_sdwa v69, v69 dst_sel:DWORD dst_unused:UNUSED_PAD src0_sel:WORD_1
	s_waitcnt vmcnt(0)
	v_cvt_f32_f16_e32 v80, v70
	v_cvt_f32_f16_sdwa v81, v70 dst_sel:DWORD dst_unused:UNUSED_PAD src0_sel:WORD_1
	v_cvt_f32_f16_e32 v70, v71
	v_cvt_f32_f16_sdwa v71, v71 dst_sel:DWORD dst_unused:UNUSED_PAD src0_sel:WORD_1
	v_cvt_f32_f16_e32 v82, v72
	v_cvt_f32_f16_sdwa v83, v72 dst_sel:DWORD dst_unused:UNUSED_PAD src0_sel:WORD_1
	v_cvt_f32_f16_e32 v72, v73
	v_cvt_f32_f16_sdwa v73, v73 dst_sel:DWORD dst_unused:UNUSED_PAD src0_sel:WORD_1
	v_pk_add_f32 v[60:61], v[60:61], v[76:77]
	v_pk_add_f32 v[62:63], v[62:63], v[66:67]
	v_pk_add_f32 v[56:57], v[56:57], v[78:79]
	v_pk_add_f32 v[58:59], v[58:59], v[68:69]
	v_pk_add_f32 v[52:53], v[52:53], v[80:81]
	v_pk_add_f32 v[54:55], v[54:55], v[70:71]
	v_pk_add_f32 v[66:67], v[48:49], v[82:83]
	v_pk_add_f32 v[68:69], v[50:51], v[72:73]
	v_pk_mul_f32 v[70:71], v[60:61], v[60:61]
	v_cvt_pk_f16_f32 v48, v60, v61
	v_pk_mul_f32 v[60:61], v[62:63], v[62:63]
	v_cvt_pk_f16_f32 v49, v62, v63
	v_pk_mul_f32 v[62:63], v[56:57], v[56:57]
	v_cvt_pk_f16_f32 v50, v56, v57
	v_pk_mul_f32 v[56:57], v[58:59], v[58:59]
	v_cvt_pk_f16_f32 v51, v58, v59
	v_pk_mul_f32 v[58:59], v[52:53], v[52:53]
	v_pk_mul_f32 v[72:73], v[54:55], v[54:55]
	v_add_f32_e32 v58, v58, v59
	v_add_f32_e32 v59, v70, v71
	v_add_f32_e32 v58, v72, v58
	v_add_f32_e32 v59, v60, v59
	v_pk_mul_f32 v[76:77], v[66:67], v[66:67]
	v_add_f32_e32 v58, v73, v58
	v_add_f32_e32 v59, v61, v59
	v_add_f32_e32 v58, v76, v58
	v_add_f32_e32 v59, v62, v59
	v_pk_mul_f32 v[78:79], v[68:69], v[68:69]
	v_add_f32_e32 v58, v77, v58
	v_add_f32_e32 v59, v63, v59
	v_add_f32_e32 v58, v78, v58
	v_add_f32_e32 v56, v56, v59
	v_add_f32_e32 v58, v79, v58
	v_add_f32_e32 v56, v57, v56
	v_add_f32_e32 v58, v56, v58
	ds_bpermute_b32 v59, v165, v58
	v_lshl_add_u64 v[56:57], s[86:87], 0, v[74:75]
	v_lshl_add_u64 v[56:57], v[56:57], 0, v[156:157]
	global_store_dwordx4 v[56:57], v[48:51], off sc0 sc1
	s_waitcnt lgkmcnt(0)
	s_nop 0
	v_add_f32_e32 v48, v58, v59
	ds_bpermute_b32 v49, v164, v48
	v_cvt_pk_f16_f32 v50, v52, v53
	v_cvt_pk_f16_f32 v51, v54, v55
	v_cvt_pk_f16_f32 v52, v66, v67
	v_cvt_pk_f16_f32 v53, v68, v69
	global_store_dwordx4 v[56:57], v[50:53], off offset:256 sc0 sc1
	s_and_saveexec_b64 s[26:27], s[6:7]
	s_cbranch_execz .LBB0_542
	v_lshl_add_u64 v[50:51], v[64:65], 2, s[14:15]
	s_waitcnt lgkmcnt(0)
	v_add_f32_e32 v48, v48, v49
	global_atomic_add_f32 v[50:51], v48, off
;     __device__ __forceinline__ void operator()(const f32x4 (&acc)[2][2][4][2], const pg8::Unit& u, int wr, int wc, int fr, int fq) const {
;     ...
;         for (int ai = 0; ai < 2; ++ai)
; #pragma unroll
;             for (int m = 0; m < 4; ++m) {
;                 const int row = row0 + ai * 128 + m * 16;
;                 float ss = 0.f, rstd = 1.f;
;                 if (MODE == 2) rstd = rsqrtf(rowss[row] * (1.f / 1024.f) + EPS);
; #pragma unroll
;                 for (int bj = 0; bj < 2; ++bj) {
;                     const int c = col0 + bj * 128;
;                     f32x4 v0 = acc[ai][bj][m][0], v1 = acc[ai][bj][m][1];
;                     if (MODE == 1) {
;                         const float* rp = res + (size_t)row * ldres + c;
;                         v0 += *(const f32x4*)rp; v1 += *(const f32x4*)(rp + 4);
;                     }
;                     if (MODE == 3) {
;                         const h16x8 r8 = *(const h16x8*)(res16 + (size_t)row * ldres + c);
; #pragma unroll
;                         for (int j = 0; j < 4; ++j) { v0[j] += (float)r8[j]; v1[j] += (float)r8[4 + j]; }
;                     }
;                     if (MODE == 1 || MODE == 3) {
;                         ss += v0[0] * v0[0] + v0[1] * v0[1] + v0[2] * v0[2] + v0[3] * v0[3] + v1[0] * v1[0] + v1[1] * v1[1] + v1[2] * v1[2] + v1[3] * v1[3];
;                     }
;                     if (MODE == 2) {
; #pragma unroll
;                         for (int j = 0; j < 4; ++j) { float a = fmaxf(v0[j] * rstd, 0.f), b = fmaxf(v1[j] * rstd, 0.f); v0[j] = a * a; v1[j] = b * b; }
;                     }
;                     *(h16x8*)(o16 + (size_t)row * ld16 + c) = pack8(v0, v1);
;                 }
;                 if (MODE == 1 || MODE == 3) {
;                     ss += __shfl_xor(ss, 16); ss += __shfl_xor(ss, 32);
;                     if (fq == 0) atomicAdd(rowss + row, ss);
;                 }
.LBB0_542:
	s_or_b64 exec, exec, s[26:27]
	v_add_u32_e32 v48, 0x90, v158
	s_waitcnt lgkmcnt(0)
	v_ashrrev_i32_e32 v49, 31, v48
	v_lshlrev_b64 v[58:59], 11, v[48:49]
	v_lshl_add_u64 v[50:51], s[10:11], 0, v[58:59]
	v_lshl_add_u64 v[54:55], v[50:51], 0, v[156:157]
	global_load_dwordx4 v[50:53], v[54:55], off
	s_nop 0
	global_load_dwordx4 v[54:57], v[54:55], off offset:256
	s_waitcnt vmcnt(1)
	v_cvt_f32_f16_e32 v60, v50
	v_cvt_f32_f16_sdwa v61, v50 dst_sel:DWORD dst_unused:UNUSED_PAD src0_sel:WORD_1
	v_cvt_f32_f16_e32 v50, v51
	v_cvt_f32_f16_sdwa v51, v51 dst_sel:DWORD dst_unused:UNUSED_PAD src0_sel:WORD_1
	v_cvt_f32_f16_e32 v62, v52
	v_cvt_f32_f16_sdwa v63, v52 dst_sel:DWORD dst_unused:UNUSED_PAD src0_sel:WORD_1
	v_cvt_f32_f16_e32 v52, v53
	v_cvt_f32_f16_sdwa v53, v53 dst_sel:DWORD dst_unused:UNUSED_PAD src0_sel:WORD_1
	s_waitcnt vmcnt(0)
	v_cvt_f32_f16_e32 v64, v54
	v_cvt_f32_f16_sdwa v65, v54 dst_sel:DWORD dst_unused:UNUSED_PAD src0_sel:WORD_1
	v_cvt_f32_f16_e32 v54, v55
	v_cvt_f32_f16_sdwa v55, v55 dst_sel:DWORD dst_unused:UNUSED_PAD src0_sel:WORD_1
	v_cvt_f32_f16_e32 v66, v56
	v_cvt_f32_f16_sdwa v67, v56 dst_sel:DWORD dst_unused:UNUSED_PAD src0_sel:WORD_1
	v_cvt_f32_f16_e32 v56, v57
	v_cvt_f32_f16_sdwa v57, v57 dst_sel:DWORD dst_unused:UNUSED_PAD src0_sel:WORD_1
	v_pk_add_f32 v[44:45], v[44:45], v[60:61]
	v_pk_add_f32 v[46:47], v[46:47], v[50:51]
	v_pk_add_f32 v[40:41], v[40:41], v[62:63]
	v_pk_add_f32 v[42:43], v[42:43], v[52:53]
	v_pk_add_f32 v[36:37], v[36:37], v[64:65]
	v_pk_add_f32 v[38:39], v[38:39], v[54:55]
	v_pk_add_f32 v[50:51], v[32:33], v[66:67]
	v_pk_add_f32 v[52:53], v[34:35], v[56:57]
	v_pk_mul_f32 v[54:55], v[44:45], v[44:45]
	v_cvt_pk_f16_f32 v32, v44, v45
	v_pk_mul_f32 v[44:45], v[46:47], v[46:47]
	v_cvt_pk_f16_f32 v33, v46, v47
	v_pk_mul_f32 v[46:47], v[40:41], v[40:41]
	v_cvt_pk_f16_f32 v34, v40, v41
	v_pk_mul_f32 v[40:41], v[42:43], v[42:43]
	v_cvt_pk_f16_f32 v35, v42, v43
	v_pk_mul_f32 v[42:43], v[36:37], v[36:37]
	v_pk_mul_f32 v[56:57], v[38:39], v[38:39]
	v_add_f32_e32 v42, v42, v43
	v_add_f32_e32 v43, v54, v55
	v_add_f32_e32 v42, v56, v42
	v_add_f32_e32 v43, v44, v43
	v_pk_mul_f32 v[60:61], v[50:51], v[50:51]
	v_add_f32_e32 v42, v57, v42
	v_add_f32_e32 v43, v45, v43
	v_add_f32_e32 v42, v60, v42
	v_add_f32_e32 v43, v46, v43
	v_pk_mul_f32 v[62:63], v[52:53], v[52:53]
	v_add_f32_e32 v42, v61, v42
	v_add_f32_e32 v43, v47, v43
	v_add_f32_e32 v42, v62, v42
	v_add_f32_e32 v40, v40, v43
	v_add_f32_e32 v42, v63, v42
	v_add_f32_e32 v40, v41, v40
	v_add_f32_e32 v42, v40, v42
	ds_bpermute_b32 v43, v165, v42
	v_lshl_add_u64 v[40:41], s[86:87], 0, v[58:59]
	v_lshl_add_u64 v[40:41], v[40:41], 0, v[156:157]
	global_store_dwordx4 v[40:41], v[32:35], off sc0 sc1
	s_waitcnt lgkmcnt(0)
	s_nop 0
	v_add_f32_e32 v32, v42, v43
	ds_bpermute_b32 v33, v164, v32
	v_cvt_pk_f16_f32 v34, v36, v37
	v_cvt_pk_f16_f32 v35, v38, v39
	v_cvt_pk_f16_f32 v36, v50, v51
	v_cvt_pk_f16_f32 v37, v52, v53
	global_store_dwordx4 v[40:41], v[34:37], off offset:256 sc0 sc1
	s_and_saveexec_b64 s[26:27], s[6:7]
	s_cbranch_execz .LBB0_544
	v_lshl_add_u64 v[34:35], v[48:49], 2, s[14:15]
	s_waitcnt lgkmcnt(0)
	v_add_f32_e32 v32, v32, v33
	global_atomic_add_f32 v[34:35], v32, off
;     __device__ __forceinline__ void operator()(const f32x4 (&acc)[2][2][4][2], const pg8::Unit& u, int wr, int wc, int fr, int fq) const {
;     ...
;         for (int ai = 0; ai < 2; ++ai)
; #pragma unroll
;             for (int m = 0; m < 4; ++m) {
;                 const int row = row0 + ai * 128 + m * 16;
;                 float ss = 0.f, rstd = 1.f;
;                 if (MODE == 2) rstd = rsqrtf(rowss[row] * (1.f / 1024.f) + EPS);
; #pragma unroll
;                 for (int bj = 0; bj < 2; ++bj) {
;                     const int c = col0 + bj * 128;
;                     f32x4 v0 = acc[ai][bj][m][0], v1 = acc[ai][bj][m][1];
;                     if (MODE == 1) {
;                         const float* rp = res + (size_t)row * ldres + c;
;                         v0 += *(const f32x4*)rp; v1 += *(const f32x4*)(rp + 4);
;                     }
;                     if (MODE == 3) {
;                         const h16x8 r8 = *(const h16x8*)(res16 + (size_t)row * ldres + c);
; #pragma unroll
;                         for (int j = 0; j < 4; ++j) { v0[j] += (float)r8[j]; v1[j] += (float)r8[4 + j]; }
;                     }
;                     if (MODE == 1 || MODE == 3) {
;                         ss += v0[0] * v0[0] + v0[1] * v0[1] + v0[2] * v0[2] + v0[3] * v0[3] + v1[0] * v1[0] + v1[1] * v1[1] + v1[2] * v1[2] + v1[3] * v1[3];
;                     }
;                     if (MODE == 2) {
; #pragma unroll
;                         for (int j = 0; j < 4; ++j) { float a = fmaxf(v0[j] * rstd, 0.f), b = fmaxf(v1[j] * rstd, 0.f); v0[j] = a * a; v1[j] = b * b; }
;                     }
;                     *(h16x8*)(o16 + (size_t)row * ld16 + c) = pack8(v0, v1);
;                 }
;                 if (MODE == 1 || MODE == 3) {
;                     ss += __shfl_xor(ss, 16); ss += __shfl_xor(ss, 32);
;                     if (fq == 0) atomicAdd(rowss + row, ss);
;                 }
.LBB0_544:
	s_or_b64 exec, exec, s[26:27]
	v_add_u32_e32 v32, 0xa0, v158
	s_waitcnt lgkmcnt(0)
	v_ashrrev_i32_e32 v33, 31, v32
	v_lshlrev_b64 v[42:43], 11, v[32:33]
	v_lshl_add_u64 v[34:35], s[10:11], 0, v[42:43]
	v_lshl_add_u64 v[38:39], v[34:35], 0, v[156:157]
	global_load_dwordx4 v[34:37], v[38:39], off
	s_nop 0
	global_load_dwordx4 v[38:41], v[38:39], off offset:256
	s_waitcnt vmcnt(1)
	v_cvt_f32_f16_e32 v44, v34
	v_cvt_f32_f16_sdwa v45, v34 dst_sel:DWORD dst_unused:UNUSED_PAD src0_sel:WORD_1
	v_cvt_f32_f16_e32 v34, v35
	v_cvt_f32_f16_sdwa v35, v35 dst_sel:DWORD dst_unused:UNUSED_PAD src0_sel:WORD_1
	v_cvt_f32_f16_e32 v46, v36
	v_cvt_f32_f16_sdwa v47, v36 dst_sel:DWORD dst_unused:UNUSED_PAD src0_sel:WORD_1
	v_cvt_f32_f16_e32 v36, v37
	v_cvt_f32_f16_sdwa v37, v37 dst_sel:DWORD dst_unused:UNUSED_PAD src0_sel:WORD_1
	s_waitcnt vmcnt(0)
	v_cvt_f32_f16_e32 v48, v38
	v_cvt_f32_f16_sdwa v49, v38 dst_sel:DWORD dst_unused:UNUSED_PAD src0_sel:WORD_1
	v_cvt_f32_f16_e32 v38, v39
	v_cvt_f32_f16_sdwa v39, v39 dst_sel:DWORD dst_unused:UNUSED_PAD src0_sel:WORD_1
	v_cvt_f32_f16_e32 v50, v40
	v_cvt_f32_f16_sdwa v51, v40 dst_sel:DWORD dst_unused:UNUSED_PAD src0_sel:WORD_1
	v_cvt_f32_f16_e32 v40, v41
	v_cvt_f32_f16_sdwa v41, v41 dst_sel:DWORD dst_unused:UNUSED_PAD src0_sel:WORD_1
	v_pk_add_f32 v[28:29], v[28:29], v[44:45]
	v_pk_add_f32 v[30:31], v[30:31], v[34:35]
	v_pk_add_f32 v[24:25], v[24:25], v[46:47]
	v_pk_add_f32 v[26:27], v[26:27], v[36:37]
	v_pk_add_f32 v[20:21], v[20:21], v[48:49]
	v_pk_add_f32 v[22:23], v[22:23], v[38:39]
	v_pk_add_f32 v[34:35], v[16:17], v[50:51]
	v_pk_add_f32 v[36:37], v[18:19], v[40:41]
	v_pk_mul_f32 v[38:39], v[28:29], v[28:29]
	v_cvt_pk_f16_f32 v16, v28, v29
	v_pk_mul_f32 v[28:29], v[30:31], v[30:31]
	v_cvt_pk_f16_f32 v17, v30, v31
	v_pk_mul_f32 v[30:31], v[24:25], v[24:25]
	v_cvt_pk_f16_f32 v18, v24, v25
	v_pk_mul_f32 v[24:25], v[26:27], v[26:27]
	v_cvt_pk_f16_f32 v19, v26, v27
	v_pk_mul_f32 v[26:27], v[20:21], v[20:21]
	v_pk_mul_f32 v[40:41], v[22:23], v[22:23]
	v_add_f32_e32 v26, v26, v27
	v_add_f32_e32 v27, v38, v39
	v_add_f32_e32 v26, v40, v26
	v_add_f32_e32 v27, v28, v27
	v_pk_mul_f32 v[44:45], v[34:35], v[34:35]
	v_add_f32_e32 v26, v41, v26
	v_add_f32_e32 v27, v29, v27
	v_add_f32_e32 v26, v44, v26
	v_add_f32_e32 v27, v30, v27
	v_pk_mul_f32 v[46:47], v[36:37], v[36:37]
	v_add_f32_e32 v26, v45, v26
	v_add_f32_e32 v27, v31, v27
	v_add_f32_e32 v26, v46, v26
	v_add_f32_e32 v24, v24, v27
	v_add_f32_e32 v26, v47, v26
	v_add_f32_e32 v24, v25, v24
	v_add_f32_e32 v26, v24, v26
	ds_bpermute_b32 v27, v165, v26
	v_lshl_add_u64 v[24:25], s[86:87], 0, v[42:43]
	v_lshl_add_u64 v[24:25], v[24:25], 0, v[156:157]
	global_store_dwordx4 v[24:25], v[16:19], off sc0 sc1
	s_waitcnt lgkmcnt(0)
	s_nop 0
	v_add_f32_e32 v16, v26, v27
	ds_bpermute_b32 v17, v164, v16
	v_cvt_pk_f16_f32 v18, v20, v21
	v_cvt_pk_f16_f32 v19, v22, v23
	v_cvt_pk_f16_f32 v20, v34, v35
	v_cvt_pk_f16_f32 v21, v36, v37
	global_store_dwordx4 v[24:25], v[18:21], off offset:256 sc0 sc1
	s_and_saveexec_b64 s[26:27], s[6:7]
	s_cbranch_execz .LBB0_546
	v_lshl_add_u64 v[18:19], v[32:33], 2, s[14:15]
	s_waitcnt lgkmcnt(0)
	v_add_f32_e32 v16, v16, v17
	global_atomic_add_f32 v[18:19], v16, off
.LBB0_546:
	s_or_b64 exec, exec, s[26:27]
	v_add_u32_e32 v16, 0xb0, v158
	s_waitcnt lgkmcnt(0)
	v_ashrrev_i32_e32 v17, 31, v16
	v_lshlrev_b64 v[26:27], 11, v[16:17]
	v_lshl_add_u64 v[18:19], s[10:11], 0, v[26:27]
	v_lshl_add_u64 v[22:23], v[18:19], 0, v[156:157]
	global_load_dwordx4 v[18:21], v[22:23], off
	s_nop 0
	global_load_dwordx4 v[22:25], v[22:23], off offset:256
	s_waitcnt vmcnt(1)
	v_cvt_f32_f16_e32 v28, v18
	v_cvt_f32_f16_sdwa v29, v18 dst_sel:DWORD dst_unused:UNUSED_PAD src0_sel:WORD_1
	v_cvt_f32_f16_e32 v18, v19
	v_cvt_f32_f16_sdwa v19, v19 dst_sel:DWORD dst_unused:UNUSED_PAD src0_sel:WORD_1
	v_cvt_f32_f16_e32 v30, v20
	v_cvt_f32_f16_sdwa v31, v20 dst_sel:DWORD dst_unused:UNUSED_PAD src0_sel:WORD_1
	v_cvt_f32_f16_e32 v20, v21
	v_cvt_f32_f16_sdwa v21, v21 dst_sel:DWORD dst_unused:UNUSED_PAD src0_sel:WORD_1
	s_waitcnt vmcnt(0)
	v_cvt_f32_f16_e32 v32, v22
	v_cvt_f32_f16_sdwa v33, v22 dst_sel:DWORD dst_unused:UNUSED_PAD src0_sel:WORD_1
	v_cvt_f32_f16_e32 v22, v23
	v_cvt_f32_f16_sdwa v23, v23 dst_sel:DWORD dst_unused:UNUSED_PAD src0_sel:WORD_1
	v_cvt_f32_f16_e32 v34, v24
	v_cvt_f32_f16_sdwa v35, v24 dst_sel:DWORD dst_unused:UNUSED_PAD src0_sel:WORD_1
	v_cvt_f32_f16_e32 v24, v25
	v_cvt_f32_f16_sdwa v25, v25 dst_sel:DWORD dst_unused:UNUSED_PAD src0_sel:WORD_1
	v_pk_add_f32 v[12:13], v[12:13], v[28:29]
	v_pk_add_f32 v[14:15], v[14:15], v[18:19]
	v_pk_add_f32 v[8:9], v[8:9], v[30:31]
	v_pk_add_f32 v[10:11], v[10:11], v[20:21]
	v_pk_add_f32 v[4:5], v[4:5], v[32:33]
	v_pk_add_f32 v[6:7], v[6:7], v[22:23]
	v_pk_add_f32 v[18:19], v[0:1], v[34:35]
	v_pk_add_f32 v[20:21], v[2:3], v[24:25]
	v_pk_mul_f32 v[22:23], v[12:13], v[12:13]
	v_cvt_pk_f16_f32 v0, v12, v13
	v_pk_mul_f32 v[12:13], v[14:15], v[14:15]
	v_cvt_pk_f16_f32 v1, v14, v15
	v_pk_mul_f32 v[14:15], v[8:9], v[8:9]
	v_cvt_pk_f16_f32 v2, v8, v9
	v_pk_mul_f32 v[8:9], v[10:11], v[10:11]
	v_cvt_pk_f16_f32 v3, v10, v11
	v_pk_mul_f32 v[10:11], v[4:5], v[4:5]
	v_pk_mul_f32 v[24:25], v[6:7], v[6:7]
	v_add_f32_e32 v10, v10, v11
	v_add_f32_e32 v11, v22, v23
	v_add_f32_e32 v10, v24, v10
	v_add_f32_e32 v11, v12, v11
	v_pk_mul_f32 v[28:29], v[18:19], v[18:19]
	v_add_f32_e32 v10, v25, v10
	v_add_f32_e32 v11, v13, v11
	v_add_f32_e32 v10, v28, v10
	v_add_f32_e32 v11, v14, v11
	v_pk_mul_f32 v[30:31], v[20:21], v[20:21]
	v_add_f32_e32 v10, v29, v10
	v_add_f32_e32 v11, v15, v11
	v_add_f32_e32 v10, v30, v10
	v_add_f32_e32 v8, v8, v11
	v_add_f32_e32 v10, v31, v10
	v_add_f32_e32 v8, v9, v8
	v_add_f32_e32 v10, v8, v10
	ds_bpermute_b32 v11, v165, v10
	v_lshl_add_u64 v[8:9], s[86:87], 0, v[26:27]
	v_lshl_add_u64 v[8:9], v[8:9], 0, v[156:157]
	global_store_dwordx4 v[8:9], v[0:3], off sc0 sc1
	s_waitcnt lgkmcnt(0)
	s_nop 0
	v_add_f32_e32 v0, v10, v11
	ds_bpermute_b32 v1, v164, v0
	v_cvt_pk_f16_f32 v2, v4, v5
	v_cvt_pk_f16_f32 v3, v6, v7
	v_cvt_pk_f16_f32 v4, v18, v19
	v_cvt_pk_f16_f32 v5, v20, v21
	global_store_dwordx4 v[8:9], v[2:5], off offset:256 sc0 sc1
	s_and_saveexec_b64 s[26:27], s[6:7]
	s_cbranch_execz .LBB0_523
	v_lshl_add_u64 v[2:3], v[16:17], 2, s[14:15]
	s_waitcnt lgkmcnt(0)
	v_add_f32_e32 v0, v0, v1
	global_atomic_add_f32 v[2:3], v0, off
	s_branch .LBB0_523

; #define LAS __attribute__((address_space(3)))
; __device__ __forceinline__ unsigned xb_add(unsigned* p, unsigned v) { return __hip_atomic_fetch_add(p, v, __ATOMIC_RELAXED, __HIP_MEMORY_SCOPE_AGENT); }
; __device__ __forceinline__ void xcd_barrier(const XB& b) {
;     __syncthreads();
;     if (threadIdx.x == 0) {
;         unsigned* bar = b.bar;
;         __builtin_amdgcn_fence(__ATOMIC_RELEASE, "agent");
;         asm volatile("s_waitcnt vmcnt(0)" ::: "memory");
;         const unsigned old = xb_add(&bar[XB_XSUB(b.x)], 1u);
;         const unsigned gen = old / b.nloc;
;         if (old + 1u == (gen + 1u) * b.nloc) {
;             const unsigned og = xb_add(&bar[XB_TOP], 1u);
; __device__ __forceinline__ void skinny_down_splitk(const Params& p, LAS unsigned char* lds) {
;     ...
;         *(LAS f32x4*)(RED + ((grp * 4 + ksp) * 64 + lane) * 4) = acc;
;         __syncthreads();
;         if (ksp == 0 && act) {
; #pragma unroll
;             for (int q = 1; q < 4; ++q) acc += *(const LAS f32x4*)(RED + ((grp * 4 + q) * 64 + lane) * 4);
;             const int row = MP + rt * 16 + fr, col = ct * 16 + fq * 4, sidx = row - MP;
;             f32x4 v = acc + *(const f32x4*)((const float*)(ws + OFF_X1) + (size_t)row * D + col);
;             *(f32x4*)(p.out + O_YS + (size_t)sidx * D + col) = v;
;             float ss = v[0] * v[0] + v[1] * v[1] + v[2] * v[2] + v[3] * v[3];
;             ss += __shfl_xor(ss, 16); ss += __shfl_xor(ss, 32);
;             if (fq == 0) atomicAdd((float*)(ws + OFF_SS2) + row, ss);
.Lsk6_done:
	s_and_b64 s[0:1], vcc, s[0:1]
	s_nop 5
	ds_write_b128 v16, v[0:3]
	s_waitcnt lgkmcnt(0)
	s_barrier
	s_and_saveexec_b64 s[8:9], s[0:1]
	s_cbranch_execz .LBB0_608
	v_or_b32_e32 v10, v21, v15
	v_lshlrev_b64 v[12:13], 12, v[4:5]
	v_ashrrev_i32_e32 v11, 31, v10
	v_lshl_add_u64 v[12:13], s[86:87], 0, v[12:13]
	v_lshlrev_b64 v[34:35], 2, v[10:11]
	v_lshl_add_u64 v[10:11], v[12:13], 0, v[34:35]
	global_load_dwordx4 v[10:13], v[10:11], off
	ds_read_b128 v[22:25], v17 offset:1024
	ds_read_b128 v[26:29], v17 offset:2048
	ds_read_b128 v[30:33], v17 offset:3072
	v_cmp_lt_i32_e64 s[0:1], v19, v135
	v_ashrrev_i32_e32 v37, 31, v4
	s_waitcnt lgkmcnt(2)
	v_pk_add_f32 v[0:1], v[0:1], v[22:23]
	v_pk_add_f32 v[2:3], v[2:3], v[24:25]
	s_waitcnt lgkmcnt(1)
	v_pk_add_f32 v[0:1], v[0:1], v[26:27]
	v_pk_add_f32 v[2:3], v[2:3], v[28:29]
	s_waitcnt lgkmcnt(0)
	v_pk_add_f32 v[0:1], v[0:1], v[30:31]
	v_pk_add_f32 v[2:3], v[2:3], v[32:33]
	v_cndmask_b32_e64 v21, v129, v19, s[0:1]
	v_lshlrev_b32_e32 v21, 2, v21
	v_mov_b32_e32 v36, v4
	v_cmp_lt_i32_e64 s[0:1], v20, v135
	s_waitcnt vmcnt(0)
	v_pk_add_f32 v[10:11], v[0:1], v[10:11]
	s_nop 0
	v_mul_f32_e32 v22, v11, v11
	v_pk_add_f32 v[12:13], v[2:3], v[12:13]
	v_fmac_f32_e32 v22, v10, v10
	v_fmac_f32_e32 v22, v12, v12
	v_fmac_f32_e32 v22, v13, v13
	ds_bpermute_b32 v21, v21, v22
	v_lshlrev_b64 v[0:1], 12, v[36:37]
	v_cndmask_b32_e64 v38, v129, v20, s[0:1]
	v_lshl_add_u64 v[0:1], s[4:5], 0, v[0:1]
	v_lshlrev_b32_e32 v23, 2, v38
	v_lshl_add_u64 v[2:3], v[0:1], 0, v[34:35]
	s_waitcnt lgkmcnt(0)
	v_add_f32_e32 v0, v22, v21
	ds_bpermute_b32 v1, v23, v0
	v_add_co_u32_e64 v2, s[0:1], s13, v2
	s_nop 1
	v_addc_co_u32_e64 v3, s[0:1], -1, v3, s[0:1]
	global_store_dwordx4 v[2:3], v[10:13], off sc0 sc1
	s_and_b64 exec, exec, s[2:3]
	s_cbranch_execz .LBB0_608
	s_waitcnt lgkmcnt(0)
	v_add_f32_e32 v2, v0, v1
	v_lshl_add_u64 v[0:1], v[4:5], 2, s[14:15]
	global_atomic_add_f32 v[0:1], v2, off
	s_branch .LBB0_608
.LBB0_618:
	s_waitcnt lgkmcnt(0)
	s_waitcnt vmcnt(0)
	s_barrier
	s_mov_b64 s[0:1], exec
	v_readlane_b32 s2, v253, 2
	v_readlane_b32 s3, v253, 3
	s_and_b64 s[2:3], s[0:1], s[2:3]
	s_mov_b64 exec, s[2:3]
	s_cbranch_execz .LBB0_637
	s_mov_b64 s[4:5], exec
	s_nop 0
	s_waitcnt vmcnt(0)
	s_waitcnt vmcnt(0)
	s_lshl_b32 s2, s89, 8
	v_readlane_b32 s6, v253, 0
	v_mbcnt_lo_u32_b32 v0, s4, 0
	v_readlane_b32 s7, v253, 1
	s_add_u32 s2, s6, s2
	v_mbcnt_hi_u32_b32 v0, s5, v0
	s_addc_u32 s3, s7, 0
	v_cmp_eq_u32_e32 vcc, 0, v0
	s_and_saveexec_b64 s[6:7], vcc
	s_cbranch_execz .LBB0_621
	s_bcnt1_i32_b64 s4, s[4:5]
	v_mov_b32_e32 v1, 0x1000
	v_mov_b32_e32 v2, s4
	global_atomic_add v1, v1, v2, s[2:3] sc0
